# all 7 GEMM K-loops: LDS-DMA staging rebalanced 4/4/4/4 (A[b][0] staged one phase later, SP2 waits vmcnt(6)); attention load hoist
# speedup vs baseline: 1.0219x; 1.0106x over previous
; #define PG8_STAGE(bufoff, gbase, voff) do { _Pragma("unroll") for (int _i = 0; _i < 2; ++_i) \
;         __builtin_amdgcn_global_load_lds((const unsigned*)((const char*)(gbase) + (voff)[_i]), (LAS unsigned*)(lds + (bufoff) + ldsw + _i * 8192), 16, 0, 0); } while (0)
; #define PG8_LDA(dst, b, h) do { _Pragma("unroll") for (int m = 0; m < 4; ++m) _Pragma("unroll") for (int k = 0; k < 2; ++k) dst[m][k] = *(const LAS bf16x8*)(lds + PG8_SA(b, h) + aoff + m * 2048 + k * 1024); } while (0)
; #define PG8_LDB(dst, b, h) do { _Pragma("unroll") for (int n = 0; n < 2; ++n) _Pragma("unroll") for (int k = 0; k < 2; ++k) dst[n][k] = *(const LAS bf16x8*)(lds + PG8_SB(b, h) + boff + n * 2048 + k * 1024); } while (0)
; #define PG8_WAIT_V(n) asm volatile("s_waitcnt vmcnt(" #n ")" ::: "memory")
; #define PG8_WAIT_L(n) asm volatile("s_waitcnt lgkmcnt(" #n ")" ::: "memory")
; #define PG8_BAR __builtin_amdgcn_s_barrier()
; #define PG8_SCHED __builtin_amdgcn_sched_barrier(0)
; template <class Epi, class Sched, bool I8 = false>
; __device__ __forceinline__ void gemm_phase(LAS unsigned char* lds, const Gemm g, const Sched& S, const Epi& E) {
;     ...
;         for (int t = 0; t < nt; t += 2) {
;             const bool last = (t == nt - 2);
;             const char* a1 = cA + (size_t)(t + 1) * kstep;
;             const char* a2 = last ? nA : cA + (size_t)(t + 2) * kstep; const char* b2 = last ? nB : cB + (size_t)(t + 2) * kstep;
;             const char* a3 = a2 + kstep; const char* b3 = b2 + kstep;
;             PG8_LDB(B0, 0, 0); PG8_LDB(B1, 0, 1); PG8_SCHED; PG8_LDA(At, 0, 0); PG8_STAGE(PG8_SA(1, 1), a1 + hstepA, voffA);
;             PG8_WAIT_V(8); PG8_WAIT_L(0); PG8_BAR; PG8_MMA(0, 0, At, B0); PG8_MMA(0, 1, At, B1); PG8_BAR; PG8_SCHED;
;             PG8_LDA(At, 0, 1); PG8_STAGE(PG8_SB(0, 0), b2, voffB); PG8_STAGE(PG8_SB(0, 1), b2 + hstepB, voffB); PG8_STAGE(PG8_SA(0, 0), a2, voffA);
;             PG8_WAIT_V(8); PG8_WAIT_L(0); PG8_BAR; PG8_MMA(1, 0, At, B0); PG8_MMA(1, 1, At, B1); PG8_BAR; PG8_SCHED;
.LBB0_1169:
	ds_read_b128 v[90:93], v169
	ds_read_b128 v[98:101], v169 offset:1024
	ds_read_b128 v[172:175], v169 offset:2048
	ds_read_b128 v[176:179], v169 offset:3072
	ds_read_b128 v[180:183], v170
	ds_read_b128 v[184:187], v170 offset:1024
	ds_read_b128 v[188:191], v170 offset:2048
	ds_read_b128 v[192:195], v170 offset:3072
	s_add_u32 s22, s20, 0x4000
	s_addc_u32 s23, s21, 0
	s_cmp_eq_u32 s53, 28
	s_cselect_b32 s26, s49, s22
	s_cselect_b32 s27, s13, s23
	s_cselect_b32 s24, s50, s51
	s_cselect_b32 s25, s11, s52
	s_add_u32 s22, s26, 0x8000
	s_addc_u32 s23, s27, 0
	s_sub_u32 s98, s20, 0x4000
	s_subb_u32 s99, s21, 0
	v_lshl_add_u64 v[158:159], s[98:99], 0, v[144:145]
	s_mov_b32 m0, s43
	s_nop 0
	global_load_lds_dwordx4 v[158:159], off
	v_lshl_add_u64 v[158:159], s[98:99], 0, v[140:141]
	s_mov_b32 m0, s44
	s_nop 0
	global_load_lds_dwordx4 v[158:159], off
	v_lshl_add_u64 v[158:159], s[20:21], 0, v[148:149]
	s_add_i32 m0, s36, 0xc000
	ds_read_b128 v[196:199], v171
	ds_read_b128 v[200:203], v171 offset:1024
	ds_read_b128 v[204:207], v171 offset:2048
	ds_read_b128 v[208:211], v171 offset:3072
	ds_read_b128 v[212:215], v171 offset:4096
	ds_read_b128 v[216:219], v171 offset:5120
	ds_read_b128 v[220:223], v171 offset:6144
	ds_read_b128 v[224:227], v171 offset:7168
	global_load_lds_dwordx4 v[158:159], off
	v_lshl_add_u64 v[158:159], s[20:21], 0, v[150:151]
	s_add_i32 m0, s36, 0xe000
	s_nop 0
	global_load_lds_dwordx4 v[158:159], off
	s_waitcnt vmcnt(8)
	s_waitcnt lgkmcnt(0)
	s_barrier
	s_setprio 1
	s_waitcnt lgkmcnt(0)
	v_mfma_i32_16x16x64_i8 v[134:137], v[90:93], v[196:199], v[134:137]
	v_mfma_i32_16x16x64_i8 v[130:133], v[172:175], v[196:199], v[130:133]
	v_mfma_i32_16x16x64_i8 v[118:121], v[90:93], v[204:207], v[118:121]
	v_mfma_i32_16x16x64_i8 v[114:117], v[172:175], v[204:207], v[114:117]
	v_mfma_i32_16x16x64_i8 v[102:105], v[90:93], v[212:215], v[102:105]
	v_mfma_i32_16x16x64_i8 v[94:97], v[172:175], v[212:215], v[94:97]
	v_mfma_i32_16x16x64_i8 v[78:81], v[90:93], v[220:223], v[78:81]
	v_mfma_i32_16x16x64_i8 v[74:77], v[172:175], v[220:223], v[74:77]
	v_mfma_i32_16x16x64_i8 v[134:137], v[98:101], v[200:203], v[134:137]
	v_mfma_i32_16x16x64_i8 v[130:133], v[176:179], v[200:203], v[130:133]
	v_mfma_i32_16x16x64_i8 v[118:121], v[98:101], v[208:211], v[118:121]
	v_mfma_i32_16x16x64_i8 v[114:117], v[176:179], v[208:211], v[114:117]
	v_mfma_i32_16x16x64_i8 v[102:105], v[98:101], v[216:219], v[102:105]
	v_mfma_i32_16x16x64_i8 v[94:97], v[176:179], v[216:219], v[94:97]
	v_mfma_i32_16x16x64_i8 v[78:81], v[98:101], v[224:227], v[78:81]
	v_mfma_i32_16x16x64_i8 v[74:77], v[176:179], v[224:227], v[74:77]
	s_setprio 0
	s_setprio 1
	v_mfma_i32_16x16x64_i8 v[126:129], v[180:183], v[196:199], v[126:129]
	v_mfma_i32_16x16x64_i8 v[122:125], v[188:191], v[196:199], v[122:125]
	v_mfma_i32_16x16x64_i8 v[110:113], v[180:183], v[204:207], v[110:113]
	v_mfma_i32_16x16x64_i8 v[106:109], v[188:191], v[204:207], v[106:109]
	v_mfma_i32_16x16x64_i8 v[86:89], v[180:183], v[212:215], v[86:89]
	v_mfma_i32_16x16x64_i8 v[82:85], v[188:191], v[212:215], v[82:85]
	v_mfma_i32_16x16x64_i8 v[70:73], v[180:183], v[220:223], v[70:73]
	v_mfma_i32_16x16x64_i8 v[66:69], v[188:191], v[220:223], v[66:69]
	v_mfma_i32_16x16x64_i8 v[126:129], v[184:187], v[200:203], v[126:129]
	v_mfma_i32_16x16x64_i8 v[122:125], v[192:195], v[200:203], v[122:125]
	v_mfma_i32_16x16x64_i8 v[110:113], v[184:187], v[208:211], v[110:113]
	v_mfma_i32_16x16x64_i8 v[106:109], v[192:195], v[208:211], v[106:109]
	v_mfma_i32_16x16x64_i8 v[86:89], v[184:187], v[216:219], v[86:89]
	v_mfma_i32_16x16x64_i8 v[82:85], v[192:195], v[216:219], v[82:85]
	v_mfma_i32_16x16x64_i8 v[70:73], v[184:187], v[224:227], v[70:73]
	v_mfma_i32_16x16x64_i8 v[66:69], v[192:195], v[224:227], v[66:69]
	s_setprio 0
	s_barrier
	s_add_i32 s54, s46, s33
	v_lshl_add_u64 v[158:159], s[24:25], 0, v[142:143]
	s_mov_b32 m0, s54
	ds_read_b128 v[196:199], v171 offset:16384
	ds_read_b128 v[200:203], v171 offset:17408
	ds_read_b128 v[204:207], v171 offset:18432
	ds_read_b128 v[208:211], v171 offset:19456
	ds_read_b128 v[212:215], v171 offset:20480
	ds_read_b128 v[216:219], v171 offset:21504
	ds_read_b128 v[220:223], v171 offset:22528
	ds_read_b128 v[224:227], v171 offset:23552
	global_load_lds_dwordx4 v[158:159], off
	s_add_i32 m0, s54, 0x2000
	s_add_u32 s54, s24, 0x4000
	v_lshl_add_u64 v[158:159], s[24:25], 0, v[138:139]
	s_addc_u32 s55, s25, 0
	s_add_i32 s56, s47, s33
	global_load_lds_dwordx4 v[158:159], off
	v_lshl_add_u64 v[158:159], s[54:55], 0, v[142:143]
	s_mov_b32 m0, s56
	s_nop 0
	global_load_lds_dwordx4 v[158:159], off
	v_lshl_add_u64 v[158:159], s[54:55], 0, v[138:139]
	s_add_i32 m0, s56, 0x2000
	s_nop 0
	global_load_lds_dwordx4 v[158:159], off
	s_waitcnt vmcnt(6)
	s_waitcnt lgkmcnt(0)
	s_barrier
; #define PG8_STAGE(bufoff, gbase, voff) do { _Pragma("unroll") for (int _i = 0; _i < 2; ++_i) \
;         __builtin_amdgcn_global_load_lds((const unsigned*)((const char*)(gbase) + (voff)[_i]), (LAS unsigned*)(lds + (bufoff) + ldsw + _i * 8192), 16, 0, 0); } while (0)
; #define PG8_LDA(dst, b, h) do { _Pragma("unroll") for (int m = 0; m < 4; ++m) _Pragma("unroll") for (int k = 0; k < 2; ++k) dst[m][k] = *(const LAS bf16x8*)(lds + PG8_SA(b, h) + aoff + m * 2048 + k * 1024); } while (0)
; #define PG8_LDB(dst, b, h) do { _Pragma("unroll") for (int n = 0; n < 2; ++n) _Pragma("unroll") for (int k = 0; k < 2; ++k) dst[n][k] = *(const LAS bf16x8*)(lds + PG8_SB(b, h) + boff + n * 2048 + k * 1024); } while (0)
; #define PG8_WAIT_V(n) asm volatile("s_waitcnt vmcnt(" #n ")" ::: "memory")
; #define PG8_WAIT_L(n) asm volatile("s_waitcnt lgkmcnt(" #n ")" ::: "memory")
; #define PG8_BAR __builtin_amdgcn_s_barrier()
; #define PG8_SCHED __builtin_amdgcn_sched_barrier(0)
; template <class Epi, class Sched, bool I8 = false>
; __device__ __forceinline__ void gemm_phase(LAS unsigned char* lds, const Gemm g, const Sched& S, const Epi& E) {
;     ...
;             PG8_WAIT_V(8); PG8_WAIT_L(0); PG8_BAR; PG8_MMA(1, 0, At, B0); PG8_MMA(1, 1, At, B1); PG8_BAR; PG8_SCHED;
;             PG8_LDB(B0, 1, 0); PG8_LDB(B1, 1, 1); PG8_SCHED; PG8_LDA(At, 1, 0); PG8_STAGE(PG8_SA(0, 1), a2 + hstepA, voffA);
;             PG8_WAIT_V(8); PG8_WAIT_L(0); PG8_BAR; PG8_MMA(0, 0, At, B0); PG8_MMA(0, 1, At, B1); PG8_BAR; PG8_SCHED;
	s_setprio 1
	s_waitcnt lgkmcnt(0)
	v_mfma_i32_16x16x64_i8 v[62:65], v[90:93], v[196:199], v[62:65]
	v_mfma_i32_16x16x64_i8 v[58:61], v[172:175], v[196:199], v[58:61]
	v_mfma_i32_16x16x64_i8 v[46:49], v[90:93], v[204:207], v[46:49]
	v_mfma_i32_16x16x64_i8 v[42:45], v[172:175], v[204:207], v[42:45]
	v_mfma_i32_16x16x64_i8 v[30:33], v[90:93], v[212:215], v[30:33]
	v_mfma_i32_16x16x64_i8 v[26:29], v[172:175], v[212:215], v[26:29]
	v_mfma_i32_16x16x64_i8 v[14:17], v[90:93], v[220:223], v[14:17]
	v_mfma_i32_16x16x64_i8 v[10:13], v[172:175], v[220:223], v[10:13]
	v_mfma_i32_16x16x64_i8 v[62:65], v[98:101], v[200:203], v[62:65]
	v_mfma_i32_16x16x64_i8 v[58:61], v[176:179], v[200:203], v[58:61]
	v_mfma_i32_16x16x64_i8 v[46:49], v[98:101], v[208:211], v[46:49]
	v_mfma_i32_16x16x64_i8 v[42:45], v[176:179], v[208:211], v[42:45]
	v_mfma_i32_16x16x64_i8 v[30:33], v[98:101], v[216:219], v[30:33]
	v_mfma_i32_16x16x64_i8 v[26:29], v[176:179], v[216:219], v[26:29]
	v_mfma_i32_16x16x64_i8 v[14:17], v[98:101], v[224:227], v[14:17]
	v_mfma_i32_16x16x64_i8 v[10:13], v[176:179], v[224:227], v[10:13]
	s_setprio 0
	s_setprio 1
	v_mfma_i32_16x16x64_i8 v[54:57], v[180:183], v[196:199], v[54:57]
	v_mfma_i32_16x16x64_i8 v[50:53], v[188:191], v[196:199], v[50:53]
	v_mfma_i32_16x16x64_i8 v[38:41], v[180:183], v[204:207], v[38:41]
	v_mfma_i32_16x16x64_i8 v[34:37], v[188:191], v[204:207], v[34:37]
	v_mfma_i32_16x16x64_i8 v[22:25], v[180:183], v[212:215], v[22:25]
	v_mfma_i32_16x16x64_i8 v[18:21], v[188:191], v[212:215], v[18:21]
	v_mfma_i32_16x16x64_i8 v[6:9], v[180:183], v[220:223], v[6:9]
	v_mfma_i32_16x16x64_i8 v[2:5], v[188:191], v[220:223], v[2:5]
	v_mfma_i32_16x16x64_i8 v[54:57], v[184:187], v[200:203], v[54:57]
	v_mfma_i32_16x16x64_i8 v[50:53], v[192:195], v[200:203], v[50:53]
	v_mfma_i32_16x16x64_i8 v[38:41], v[184:187], v[208:211], v[38:41]
	v_mfma_i32_16x16x64_i8 v[34:37], v[192:195], v[208:211], v[34:37]
	v_mfma_i32_16x16x64_i8 v[22:25], v[184:187], v[216:219], v[22:25]
	v_mfma_i32_16x16x64_i8 v[18:21], v[192:195], v[216:219], v[18:21]
	v_mfma_i32_16x16x64_i8 v[6:9], v[184:187], v[224:227], v[6:9]
	v_mfma_i32_16x16x64_i8 v[2:5], v[192:195], v[224:227], v[2:5]
	s_setprio 0
	s_barrier
	s_add_i32 s54, 0, 0x18000
	v_add_u32_e32 v146, s54, v165
	s_add_i32 s55, 0, 0x1c000
	ds_read_b128 v[90:93], v146
	ds_read_b128 v[98:101], v146 offset:1024
	ds_read_b128 v[172:175], v146 offset:2048
	ds_read_b128 v[176:179], v146 offset:3072
	v_add_u32_e32 v146, s55, v165
	ds_read_b128 v[180:183], v146
	ds_read_b128 v[184:187], v146 offset:1024
	ds_read_b128 v[188:191], v146 offset:2048
	ds_read_b128 v[192:195], v146 offset:3072
	v_lshl_add_u64 v[158:159], s[26:27], 0, v[144:145]
	s_mov_b32 m0, s36
	s_nop 0
	global_load_lds_dwordx4 v[158:159], off
	v_lshl_add_u64 v[158:159], s[26:27], 0, v[140:141]
	s_mov_b32 m0, s37
	s_nop 0
	global_load_lds_dwordx4 v[158:159], off
	s_add_u32 s26, s26, 0x4000
	s_addc_u32 s27, s27, 0
	s_mov_b32 m0, s38
	v_lshl_add_u64 v[158:159], s[26:27], 0, v[144:145]
	ds_read_b128 v[196:199], v171 offset:32768
	ds_read_b128 v[200:203], v171 offset:33792
	ds_read_b128 v[204:207], v171 offset:34816
	ds_read_b128 v[208:211], v171 offset:35840
	ds_read_b128 v[212:215], v171 offset:36864
	ds_read_b128 v[216:219], v171 offset:37888
	ds_read_b128 v[220:223], v171 offset:38912
	ds_read_b128 v[224:227], v171 offset:39936
	global_load_lds_dwordx4 v[158:159], off
	v_lshl_add_u64 v[158:159], s[26:27], 0, v[140:141]
	s_mov_b32 m0, s39
	s_nop 0
	global_load_lds_dwordx4 v[158:159], off
	s_waitcnt vmcnt(8)
	s_waitcnt lgkmcnt(0)
	s_barrier
; #define PG8_STAGE(bufoff, gbase, voff) do { _Pragma("unroll") for (int _i = 0; _i < 2; ++_i) \
;         __builtin_amdgcn_global_load_lds((const unsigned*)((const char*)(gbase) + (voff)[_i]), (LAS unsigned*)(lds + (bufoff) + ldsw + _i * 8192), 16, 0, 0); } while (0)
; #define PG8_LDA(dst, b, h) do { _Pragma("unroll") for (int m = 0; m < 4; ++m) _Pragma("unroll") for (int k = 0; k < 2; ++k) dst[m][k] = *(const LAS bf16x8*)(lds + PG8_SA(b, h) + aoff + m * 2048 + k * 1024); } while (0)
; #define PG8_WAIT_V(n) asm volatile("s_waitcnt vmcnt(" #n ")" ::: "memory")
; #define PG8_WAIT_L(n) asm volatile("s_waitcnt lgkmcnt(" #n ")" ::: "memory")
; #define PG8_BAR __builtin_amdgcn_s_barrier()
; #define PG8_SCHED __builtin_amdgcn_sched_barrier(0)
; template <class Epi, class Sched, bool I8 = false>
; __device__ __forceinline__ void gemm_phase(LAS unsigned char* lds, const Gemm g, const Sched& S, const Epi& E) {
;     ...
;             PG8_WAIT_V(8); PG8_WAIT_L(0); PG8_BAR; PG8_MMA(0, 0, At, B0); PG8_MMA(0, 1, At, B1); PG8_BAR; PG8_SCHED;
;             PG8_LDA(At, 1, 1); PG8_STAGE(PG8_SB(1, 0), b3, voffB); PG8_STAGE(PG8_SB(1, 1), b3 + hstepB, voffB); PG8_STAGE(PG8_SA(1, 0), a3, voffA);
;             PG8_WAIT_V(8); PG8_WAIT_L(0); PG8_BAR; PG8_MMA(1, 0, At, B0); PG8_MMA(1, 1, At, B1); PG8_BAR; PG8_SCHED;
;         }
	s_setprio 1
	s_waitcnt lgkmcnt(0)
	v_mfma_i32_16x16x64_i8 v[134:137], v[90:93], v[196:199], v[134:137]
	v_mfma_i32_16x16x64_i8 v[130:133], v[172:175], v[196:199], v[130:133]
	v_mfma_i32_16x16x64_i8 v[118:121], v[90:93], v[204:207], v[118:121]
	v_mfma_i32_16x16x64_i8 v[114:117], v[172:175], v[204:207], v[114:117]
	v_mfma_i32_16x16x64_i8 v[102:105], v[90:93], v[212:215], v[102:105]
	v_mfma_i32_16x16x64_i8 v[94:97], v[172:175], v[212:215], v[94:97]
	v_mfma_i32_16x16x64_i8 v[78:81], v[90:93], v[220:223], v[78:81]
	v_mfma_i32_16x16x64_i8 v[74:77], v[172:175], v[220:223], v[74:77]
	v_mfma_i32_16x16x64_i8 v[134:137], v[98:101], v[200:203], v[134:137]
	v_mfma_i32_16x16x64_i8 v[130:133], v[176:179], v[200:203], v[130:133]
	v_mfma_i32_16x16x64_i8 v[118:121], v[98:101], v[208:211], v[118:121]
	v_mfma_i32_16x16x64_i8 v[114:117], v[176:179], v[208:211], v[114:117]
	v_mfma_i32_16x16x64_i8 v[102:105], v[98:101], v[216:219], v[102:105]
	v_mfma_i32_16x16x64_i8 v[94:97], v[176:179], v[216:219], v[94:97]
	v_mfma_i32_16x16x64_i8 v[78:81], v[98:101], v[224:227], v[78:81]
	v_mfma_i32_16x16x64_i8 v[74:77], v[176:179], v[224:227], v[74:77]
	s_setprio 0
	s_setprio 1
	v_mfma_i32_16x16x64_i8 v[126:129], v[180:183], v[196:199], v[126:129]
	v_mfma_i32_16x16x64_i8 v[122:125], v[188:191], v[196:199], v[122:125]
	v_mfma_i32_16x16x64_i8 v[110:113], v[180:183], v[204:207], v[110:113]
	v_mfma_i32_16x16x64_i8 v[106:109], v[188:191], v[204:207], v[106:109]
	v_mfma_i32_16x16x64_i8 v[86:89], v[180:183], v[212:215], v[86:89]
	v_mfma_i32_16x16x64_i8 v[82:85], v[188:191], v[212:215], v[82:85]
	v_mfma_i32_16x16x64_i8 v[70:73], v[180:183], v[220:223], v[70:73]
	v_mfma_i32_16x16x64_i8 v[66:69], v[188:191], v[220:223], v[66:69]
	v_mfma_i32_16x16x64_i8 v[126:129], v[184:187], v[200:203], v[126:129]
	v_mfma_i32_16x16x64_i8 v[122:125], v[192:195], v[200:203], v[122:125]
	v_mfma_i32_16x16x64_i8 v[110:113], v[184:187], v[208:211], v[110:113]
	v_mfma_i32_16x16x64_i8 v[106:109], v[192:195], v[208:211], v[106:109]
	v_mfma_i32_16x16x64_i8 v[86:89], v[184:187], v[216:219], v[86:89]
	v_mfma_i32_16x16x64_i8 v[82:85], v[192:195], v[216:219], v[82:85]
	v_mfma_i32_16x16x64_i8 v[70:73], v[184:187], v[224:227], v[70:73]
	v_mfma_i32_16x16x64_i8 v[66:69], v[192:195], v[224:227], v[66:69]
	s_setprio 0
	s_barrier
	s_add_u32 s26, s24, 0x8000
	s_addc_u32 s27, s25, 0
	s_add_i32 s54, s54, s33
	v_lshl_add_u64 v[158:159], s[26:27], 0, v[142:143]
	s_mov_b32 m0, s54
	ds_read_b128 v[196:199], v171 offset:49152
	ds_read_b128 v[200:203], v171 offset:50176
	ds_read_b128 v[204:207], v171 offset:51200
	ds_read_b128 v[208:211], v171 offset:52224
	ds_read_b128 v[212:215], v171 offset:53248
	ds_read_b128 v[216:219], v171 offset:54272
	ds_read_b128 v[220:223], v171 offset:55296
	ds_read_b128 v[224:227], v171 offset:56320
	global_load_lds_dwordx4 v[158:159], off
	s_add_i32 m0, s54, 0x2000
	s_add_u32 s24, s24, 0xc000
	v_lshl_add_u64 v[158:159], s[26:27], 0, v[138:139]
	s_addc_u32 s25, s25, 0
	s_add_i32 s26, s55, s33
	global_load_lds_dwordx4 v[158:159], off
	v_lshl_add_u64 v[158:159], s[24:25], 0, v[142:143]
	s_mov_b32 m0, s26
	s_nop 0
	global_load_lds_dwordx4 v[158:159], off
	v_lshl_add_u64 v[158:159], s[24:25], 0, v[138:139]
	s_add_i32 m0, s26, 0x2000
	s_nop 0
	global_load_lds_dwordx4 v[158:159], off
	s_waitcnt vmcnt(6)
	s_waitcnt lgkmcnt(0)
	s_barrier
	s_setprio 1
	s_waitcnt lgkmcnt(0)
	v_mfma_i32_16x16x64_i8 v[62:65], v[90:93], v[196:199], v[62:65]
	v_mfma_i32_16x16x64_i8 v[58:61], v[172:175], v[196:199], v[58:61]
	v_mfma_i32_16x16x64_i8 v[46:49], v[90:93], v[204:207], v[46:49]
	v_mfma_i32_16x16x64_i8 v[42:45], v[172:175], v[204:207], v[42:45]
	v_mfma_i32_16x16x64_i8 v[30:33], v[90:93], v[212:215], v[30:33]
	v_mfma_i32_16x16x64_i8 v[26:29], v[172:175], v[212:215], v[26:29]
	v_mfma_i32_16x16x64_i8 v[14:17], v[90:93], v[220:223], v[14:17]
	v_mfma_i32_16x16x64_i8 v[10:13], v[172:175], v[220:223], v[10:13]
	v_mfma_i32_16x16x64_i8 v[62:65], v[98:101], v[200:203], v[62:65]
	v_mfma_i32_16x16x64_i8 v[58:61], v[176:179], v[200:203], v[58:61]
	v_mfma_i32_16x16x64_i8 v[46:49], v[98:101], v[208:211], v[46:49]
	v_mfma_i32_16x16x64_i8 v[42:45], v[176:179], v[208:211], v[42:45]
	v_mfma_i32_16x16x64_i8 v[30:33], v[98:101], v[216:219], v[30:33]
	v_mfma_i32_16x16x64_i8 v[26:29], v[176:179], v[216:219], v[26:29]
	v_mfma_i32_16x16x64_i8 v[14:17], v[98:101], v[224:227], v[14:17]
	v_mfma_i32_16x16x64_i8 v[10:13], v[176:179], v[224:227], v[10:13]
	s_setprio 0
	s_setprio 1
	v_mfma_i32_16x16x64_i8 v[54:57], v[180:183], v[196:199], v[54:57]
	v_mfma_i32_16x16x64_i8 v[50:53], v[188:191], v[196:199], v[50:53]
	v_mfma_i32_16x16x64_i8 v[38:41], v[180:183], v[204:207], v[38:41]
	v_mfma_i32_16x16x64_i8 v[34:37], v[188:191], v[204:207], v[34:37]
	v_mfma_i32_16x16x64_i8 v[22:25], v[180:183], v[212:215], v[22:25]
	v_mfma_i32_16x16x64_i8 v[18:21], v[188:191], v[212:215], v[18:21]
	v_mfma_i32_16x16x64_i8 v[6:9], v[180:183], v[220:223], v[6:9]
	v_mfma_i32_16x16x64_i8 v[2:5], v[188:191], v[220:223], v[2:5]
	v_mfma_i32_16x16x64_i8 v[54:57], v[184:187], v[200:203], v[54:57]
	v_mfma_i32_16x16x64_i8 v[50:53], v[192:195], v[200:203], v[50:53]
	v_mfma_i32_16x16x64_i8 v[38:41], v[184:187], v[208:211], v[38:41]
	v_mfma_i32_16x16x64_i8 v[34:37], v[192:195], v[208:211], v[34:37]
	v_mfma_i32_16x16x64_i8 v[22:25], v[184:187], v[216:219], v[22:25]
	v_mfma_i32_16x16x64_i8 v[18:21], v[192:195], v[216:219], v[18:21]
	v_mfma_i32_16x16x64_i8 v[6:9], v[184:187], v[224:227], v[6:9]
	v_mfma_i32_16x16x64_i8 v[2:5], v[192:195], v[224:227], v[2:5]
	s_setprio 0
	s_barrier
	s_add_i32 s53, s53, 2
	s_add_u32 s20, s20, 0x10000
	s_addc_u32 s21, s21, 0
	s_add_u32 s51, s51, 0x10000
	s_addc_u32 s52, s52, 0
	s_cmp_gt_u32 s53, 29
	s_cbranch_scc0 .LBB0_1169
	s_and_b64 vcc, exec, s[8:9]
	s_cbranch_vccz .LBB0_1172
	s_barrier

; #define PG8_STAGE(bufoff, gbase, voff) do { _Pragma("unroll") for (int _i = 0; _i < 2; ++_i) \
;         __builtin_amdgcn_global_load_lds((const unsigned*)((const char*)(gbase) + (voff)[_i]), (LAS unsigned*)(lds + (bufoff) + ldsw + _i * 8192), 16, 0, 0); } while (0)
; #define PG8_LDA(dst, b, h) do { _Pragma("unroll") for (int m = 0; m < 4; ++m) _Pragma("unroll") for (int k = 0; k < 2; ++k) dst[m][k] = *(const LAS bf16x8*)(lds + PG8_SA(b, h) + aoff + m * 2048 + k * 1024); } while (0)
; #define PG8_LDB(dst, b, h) do { _Pragma("unroll") for (int n = 0; n < 2; ++n) _Pragma("unroll") for (int k = 0; k < 2; ++k) dst[n][k] = *(const LAS bf16x8*)(lds + PG8_SB(b, h) + boff + n * 2048 + k * 1024); } while (0)
; #define PG8_WAIT_V(n) asm volatile("s_waitcnt vmcnt(" #n ")" ::: "memory")
; #define PG8_WAIT_L(n) asm volatile("s_waitcnt lgkmcnt(" #n ")" ::: "memory")
; #define PG8_BAR __builtin_amdgcn_s_barrier()
; #define PG8_SCHED __builtin_amdgcn_sched_barrier(0)
; template <class Epi, class Sched, bool I8 = false>
; __device__ __forceinline__ void gemm_phase(LAS unsigned char* lds, const Gemm g, const Sched& S, const Epi& E) {
;     ...
;         for (int t = 0; t < nt; t += 2) {
;             const bool last = (t == nt - 2);
;             const char* a1 = cA + (size_t)(t + 1) * kstep;
;             const char* a2 = last ? nA : cA + (size_t)(t + 2) * kstep; const char* b2 = last ? nB : cB + (size_t)(t + 2) * kstep;
;             const char* a3 = a2 + kstep; const char* b3 = b2 + kstep;
;             PG8_LDB(B0, 0, 0); PG8_LDB(B1, 0, 1); PG8_SCHED; PG8_LDA(At, 0, 0); PG8_STAGE(PG8_SA(1, 1), a1 + hstepA, voffA);
;             PG8_WAIT_V(8); PG8_WAIT_L(0); PG8_BAR; PG8_MMA(0, 0, At, B0); PG8_MMA(0, 1, At, B1); PG8_BAR; PG8_SCHED;
;             PG8_LDA(At, 0, 1); PG8_STAGE(PG8_SB(0, 0), b2, voffB); PG8_STAGE(PG8_SB(0, 1), b2 + hstepB, voffB); PG8_STAGE(PG8_SA(0, 0), a2, voffA);
;             PG8_WAIT_V(8); PG8_WAIT_L(0); PG8_BAR; PG8_MMA(1, 0, At, B0); PG8_MMA(1, 1, At, B1); PG8_BAR; PG8_SCHED;
.LBB0_1393:
	ds_read_b128 v[66:69], v180
	ds_read_b128 v[70:73], v180 offset:1024
	ds_read_b128 v[74:77], v180 offset:2048
	ds_read_b128 v[78:81], v180 offset:3072
	ds_read_b128 v[146:149], v181
	ds_read_b128 v[150:153], v181 offset:1024
	ds_read_b128 v[174:177], v181 offset:2048
	ds_read_b128 v[184:187], v181 offset:3072
	s_add_u32 s20, s18, 0x4000
	s_addc_u32 s21, s19, 0
	s_cmpk_eq_i32 s49, 0x52
	s_cselect_b32 s24, s0, s20
	s_cselect_b32 s25, s1, s21
	s_cselect_b32 s22, s16, s47
	s_cselect_b32 s23, s17, s48
	s_add_u32 s20, s24, 0x8000
	s_addc_u32 s21, s25, 0
	s_sub_u32 s98, s18, 0x4000
	s_subb_u32 s99, s19, 0
	v_lshl_add_u64 v[220:221], s[98:99], 0, v[156:157]
	s_mov_b32 m0, s37
	s_nop 0
	global_load_lds_dwordx4 v[220:221], off
	v_lshl_add_u64 v[220:221], s[98:99], 0, v[160:161]
	s_mov_b32 m0, s38
	s_nop 0
	global_load_lds_dwordx4 v[220:221], off
	v_lshl_add_u64 v[220:221], s[18:19], 0, v[166:167]
	s_add_i32 m0, s31, 0xc000
	ds_read_b128 v[188:191], v182
	ds_read_b128 v[192:195], v182 offset:1024
	ds_read_b128 v[196:199], v182 offset:2048
	ds_read_b128 v[200:203], v182 offset:3072
	ds_read_b128 v[204:207], v182 offset:4096
	ds_read_b128 v[208:211], v182 offset:5120
	ds_read_b128 v[212:215], v182 offset:6144
	ds_read_b128 v[216:219], v182 offset:7168
	global_load_lds_dwordx4 v[220:221], off
	v_lshl_add_u64 v[220:221], s[18:19], 0, v[168:169]
	s_add_i32 m0, s31, 0xe000
	s_nop 0
	global_load_lds_dwordx4 v[220:221], off
	s_waitcnt vmcnt(8)
	s_waitcnt lgkmcnt(0)
	s_barrier
	s_setprio 1
	s_waitcnt lgkmcnt(0)
	v_mfma_i32_16x16x64_i8 v[142:145], v[66:69], v[188:191], v[142:145]
	v_mfma_i32_16x16x64_i8 v[138:141], v[74:77], v[188:191], v[138:141]
	v_mfma_i32_16x16x64_i8 v[126:129], v[66:69], v[196:199], v[126:129]
	v_mfma_i32_16x16x64_i8 v[122:125], v[74:77], v[196:199], v[122:125]
	v_mfma_i32_16x16x64_i8 v[110:113], v[66:69], v[204:207], v[110:113]
	v_mfma_i32_16x16x64_i8 v[106:109], v[74:77], v[204:207], v[106:109]
	v_mfma_i32_16x16x64_i8 v[94:97], v[66:69], v[212:215], v[94:97]
	v_mfma_i32_16x16x64_i8 v[90:93], v[74:77], v[212:215], v[90:93]
	v_mfma_i32_16x16x64_i8 v[142:145], v[70:73], v[192:195], v[142:145]
	v_mfma_i32_16x16x64_i8 v[138:141], v[78:81], v[192:195], v[138:141]
	v_mfma_i32_16x16x64_i8 v[126:129], v[70:73], v[200:203], v[126:129]
	v_mfma_i32_16x16x64_i8 v[122:125], v[78:81], v[200:203], v[122:125]
	v_mfma_i32_16x16x64_i8 v[110:113], v[70:73], v[208:211], v[110:113]
	v_mfma_i32_16x16x64_i8 v[106:109], v[78:81], v[208:211], v[106:109]
	v_mfma_i32_16x16x64_i8 v[94:97], v[70:73], v[216:219], v[94:97]
	v_mfma_i32_16x16x64_i8 v[90:93], v[78:81], v[216:219], v[90:93]
	s_setprio 0
	s_setprio 1
	v_mfma_i32_16x16x64_i8 v[134:137], v[146:149], v[188:191], v[134:137]
	v_mfma_i32_16x16x64_i8 v[130:133], v[174:177], v[188:191], v[130:133]
	v_mfma_i32_16x16x64_i8 v[118:121], v[146:149], v[196:199], v[118:121]
	v_mfma_i32_16x16x64_i8 v[114:117], v[174:177], v[196:199], v[114:117]
	v_mfma_i32_16x16x64_i8 v[102:105], v[146:149], v[204:207], v[102:105]
	v_mfma_i32_16x16x64_i8 v[98:101], v[174:177], v[204:207], v[98:101]
	v_mfma_i32_16x16x64_i8 v[86:89], v[146:149], v[212:215], v[86:89]
	v_mfma_i32_16x16x64_i8 v[82:85], v[174:177], v[212:215], v[82:85]
	v_mfma_i32_16x16x64_i8 v[134:137], v[150:153], v[192:195], v[134:137]
	v_mfma_i32_16x16x64_i8 v[130:133], v[184:187], v[192:195], v[130:133]
	v_mfma_i32_16x16x64_i8 v[118:121], v[150:153], v[200:203], v[118:121]
	v_mfma_i32_16x16x64_i8 v[114:117], v[184:187], v[200:203], v[114:117]
	v_mfma_i32_16x16x64_i8 v[102:105], v[150:153], v[208:211], v[102:105]
	v_mfma_i32_16x16x64_i8 v[98:101], v[184:187], v[208:211], v[98:101]
	v_mfma_i32_16x16x64_i8 v[86:89], v[150:153], v[216:219], v[86:89]
	v_mfma_i32_16x16x64_i8 v[82:85], v[184:187], v[216:219], v[82:85]
	s_setprio 0
	s_barrier
	s_add_i32 s50, s41, s30
	v_lshl_add_u64 v[220:221], s[22:23], 0, v[158:159]
	s_mov_b32 m0, s50
	ds_read_b128 v[188:191], v182 offset:16384
	ds_read_b128 v[192:195], v182 offset:17408
	ds_read_b128 v[196:199], v182 offset:18432
	ds_read_b128 v[200:203], v182 offset:19456
	ds_read_b128 v[204:207], v182 offset:20480
	ds_read_b128 v[208:211], v182 offset:21504
	ds_read_b128 v[212:215], v182 offset:22528
	ds_read_b128 v[216:219], v182 offset:23552
	global_load_lds_dwordx4 v[220:221], off
	s_add_i32 m0, s50, 0x2000
	s_add_u32 s50, s22, 0x4000
	v_lshl_add_u64 v[220:221], s[22:23], 0, v[162:163]
	s_addc_u32 s51, s23, 0
	s_add_i32 s52, s42, s30
	global_load_lds_dwordx4 v[220:221], off
	v_lshl_add_u64 v[220:221], s[50:51], 0, v[158:159]
	s_mov_b32 m0, s52
	s_nop 0
	global_load_lds_dwordx4 v[220:221], off
	v_lshl_add_u64 v[220:221], s[50:51], 0, v[162:163]
	s_add_i32 m0, s52, 0x2000
	s_nop 0
	global_load_lds_dwordx4 v[220:221], off
	s_waitcnt vmcnt(6)
	s_waitcnt lgkmcnt(0)
	s_barrier
; #define PG8_STAGE(bufoff, gbase, voff) do { _Pragma("unroll") for (int _i = 0; _i < 2; ++_i) \
;         __builtin_amdgcn_global_load_lds((const unsigned*)((const char*)(gbase) + (voff)[_i]), (LAS unsigned*)(lds + (bufoff) + ldsw + _i * 8192), 16, 0, 0); } while (0)
; #define PG8_LDA(dst, b, h) do { _Pragma("unroll") for (int m = 0; m < 4; ++m) _Pragma("unroll") for (int k = 0; k < 2; ++k) dst[m][k] = *(const LAS bf16x8*)(lds + PG8_SA(b, h) + aoff + m * 2048 + k * 1024); } while (0)
; #define PG8_LDB(dst, b, h) do { _Pragma("unroll") for (int n = 0; n < 2; ++n) _Pragma("unroll") for (int k = 0; k < 2; ++k) dst[n][k] = *(const LAS bf16x8*)(lds + PG8_SB(b, h) + boff + n * 2048 + k * 1024); } while (0)
; #define PG8_WAIT_V(n) asm volatile("s_waitcnt vmcnt(" #n ")" ::: "memory")
; #define PG8_WAIT_L(n) asm volatile("s_waitcnt lgkmcnt(" #n ")" ::: "memory")
; #define PG8_BAR __builtin_amdgcn_s_barrier()
; #define PG8_SCHED __builtin_amdgcn_sched_barrier(0)
; template <class Epi, class Sched, bool I8 = false>
; __device__ __forceinline__ void gemm_phase(LAS unsigned char* lds, const Gemm g, const Sched& S, const Epi& E) {
;     ...
;             PG8_WAIT_V(8); PG8_WAIT_L(0); PG8_BAR; PG8_MMA(1, 0, At, B0); PG8_MMA(1, 1, At, B1); PG8_BAR; PG8_SCHED;
;             PG8_LDB(B0, 1, 0); PG8_LDB(B1, 1, 1); PG8_SCHED; PG8_LDA(At, 1, 0); PG8_STAGE(PG8_SA(0, 1), a2 + hstepA, voffA);
;             PG8_WAIT_V(8); PG8_WAIT_L(0); PG8_BAR; PG8_MMA(0, 0, At, B0); PG8_MMA(0, 1, At, B1); PG8_BAR; PG8_SCHED;
	s_setprio 1
	s_waitcnt lgkmcnt(0)
	v_mfma_i32_16x16x64_i8 v[62:65], v[66:69], v[188:191], v[62:65]
	v_mfma_i32_16x16x64_i8 v[58:61], v[74:77], v[188:191], v[58:61]
	v_mfma_i32_16x16x64_i8 v[46:49], v[66:69], v[196:199], v[46:49]
	v_mfma_i32_16x16x64_i8 v[42:45], v[74:77], v[196:199], v[42:45]
	v_mfma_i32_16x16x64_i8 v[30:33], v[66:69], v[204:207], v[30:33]
	v_mfma_i32_16x16x64_i8 v[26:29], v[74:77], v[204:207], v[26:29]
	v_mfma_i32_16x16x64_i8 v[14:17], v[66:69], v[212:215], v[14:17]
	v_mfma_i32_16x16x64_i8 v[10:13], v[74:77], v[212:215], v[10:13]
	v_mfma_i32_16x16x64_i8 v[62:65], v[70:73], v[192:195], v[62:65]
	v_mfma_i32_16x16x64_i8 v[58:61], v[78:81], v[192:195], v[58:61]
	v_mfma_i32_16x16x64_i8 v[46:49], v[70:73], v[200:203], v[46:49]
	v_mfma_i32_16x16x64_i8 v[42:45], v[78:81], v[200:203], v[42:45]
	v_mfma_i32_16x16x64_i8 v[30:33], v[70:73], v[208:211], v[30:33]
	v_mfma_i32_16x16x64_i8 v[26:29], v[78:81], v[208:211], v[26:29]
	v_mfma_i32_16x16x64_i8 v[14:17], v[70:73], v[216:219], v[14:17]
	v_mfma_i32_16x16x64_i8 v[10:13], v[78:81], v[216:219], v[10:13]
	s_setprio 0
	s_setprio 1
	v_mfma_i32_16x16x64_i8 v[54:57], v[146:149], v[188:191], v[54:57]
	v_mfma_i32_16x16x64_i8 v[50:53], v[174:177], v[188:191], v[50:53]
	v_mfma_i32_16x16x64_i8 v[38:41], v[146:149], v[196:199], v[38:41]
	v_mfma_i32_16x16x64_i8 v[34:37], v[174:177], v[196:199], v[34:37]
	v_mfma_i32_16x16x64_i8 v[22:25], v[146:149], v[204:207], v[22:25]
	v_mfma_i32_16x16x64_i8 v[18:21], v[174:177], v[204:207], v[18:21]
	v_mfma_i32_16x16x64_i8 v[6:9], v[146:149], v[212:215], v[6:9]
	v_mfma_i32_16x16x64_i8 v[2:5], v[174:177], v[212:215], v[2:5]
	v_mfma_i32_16x16x64_i8 v[54:57], v[150:153], v[192:195], v[54:57]
	v_mfma_i32_16x16x64_i8 v[50:53], v[184:187], v[192:195], v[50:53]
	v_mfma_i32_16x16x64_i8 v[38:41], v[150:153], v[200:203], v[38:41]
	v_mfma_i32_16x16x64_i8 v[34:37], v[184:187], v[200:203], v[34:37]
	v_mfma_i32_16x16x64_i8 v[22:25], v[150:153], v[208:211], v[22:25]
	v_mfma_i32_16x16x64_i8 v[18:21], v[184:187], v[208:211], v[18:21]
	v_mfma_i32_16x16x64_i8 v[6:9], v[150:153], v[216:219], v[6:9]
	v_mfma_i32_16x16x64_i8 v[2:5], v[184:187], v[216:219], v[2:5]
	s_setprio 0
	s_barrier
	s_add_i32 s50, 0, 0x18000
	s_add_i32 s51, 0, 0x1c000
	v_add_u32_e32 v78, s50, v178
	v_add_u32_e32 v164, s51, v178
	ds_read_b128 v[66:69], v78
	ds_read_b128 v[70:73], v78 offset:1024
	ds_read_b128 v[74:77], v78 offset:2048
	ds_read_b128 v[78:81], v78 offset:3072
	ds_read_b128 v[146:149], v164
	ds_read_b128 v[150:153], v164 offset:1024
	ds_read_b128 v[174:177], v164 offset:2048
	ds_read_b128 v[184:187], v164 offset:3072
	v_lshl_add_u64 v[220:221], s[24:25], 0, v[156:157]
	s_mov_b32 m0, s31
	s_nop 0
	global_load_lds_dwordx4 v[220:221], off
	v_lshl_add_u64 v[220:221], s[24:25], 0, v[160:161]
	s_mov_b32 m0, s33
	s_nop 0
	global_load_lds_dwordx4 v[220:221], off
	s_add_u32 s24, s24, 0x4000
	s_addc_u32 s25, s25, 0
	s_mov_b32 m0, s34
	v_lshl_add_u64 v[220:221], s[24:25], 0, v[156:157]
	ds_read_b128 v[188:191], v182 offset:32768
	ds_read_b128 v[192:195], v182 offset:33792
	ds_read_b128 v[196:199], v182 offset:34816
	ds_read_b128 v[200:203], v182 offset:35840
	ds_read_b128 v[204:207], v182 offset:36864
	ds_read_b128 v[208:211], v182 offset:37888
	ds_read_b128 v[212:215], v182 offset:38912
	ds_read_b128 v[216:219], v182 offset:39936
	global_load_lds_dwordx4 v[220:221], off
	v_lshl_add_u64 v[220:221], s[24:25], 0, v[160:161]
	s_mov_b32 m0, s35
	s_nop 0
	global_load_lds_dwordx4 v[220:221], off
	s_waitcnt vmcnt(8)
	s_waitcnt lgkmcnt(0)
	s_barrier
; #define PG8_STAGE(bufoff, gbase, voff) do { _Pragma("unroll") for (int _i = 0; _i < 2; ++_i) \
;         __builtin_amdgcn_global_load_lds((const unsigned*)((const char*)(gbase) + (voff)[_i]), (LAS unsigned*)(lds + (bufoff) + ldsw + _i * 8192), 16, 0, 0); } while (0)
; #define PG8_LDA(dst, b, h) do { _Pragma("unroll") for (int m = 0; m < 4; ++m) _Pragma("unroll") for (int k = 0; k < 2; ++k) dst[m][k] = *(const LAS bf16x8*)(lds + PG8_SA(b, h) + aoff + m * 2048 + k * 1024); } while (0)
; #define PG8_WAIT_V(n) asm volatile("s_waitcnt vmcnt(" #n ")" ::: "memory")
; #define PG8_WAIT_L(n) asm volatile("s_waitcnt lgkmcnt(" #n ")" ::: "memory")
; #define PG8_BAR __builtin_amdgcn_s_barrier()
; #define PG8_SCHED __builtin_amdgcn_sched_barrier(0)
; template <class Epi, class Sched, bool I8 = false>
; __device__ __forceinline__ void gemm_phase(LAS unsigned char* lds, const Gemm g, const Sched& S, const Epi& E) {
;     ...
;             PG8_WAIT_V(8); PG8_WAIT_L(0); PG8_BAR; PG8_MMA(0, 0, At, B0); PG8_MMA(0, 1, At, B1); PG8_BAR; PG8_SCHED;
;             PG8_LDA(At, 1, 1); PG8_STAGE(PG8_SB(1, 0), b3, voffB); PG8_STAGE(PG8_SB(1, 1), b3 + hstepB, voffB); PG8_STAGE(PG8_SA(1, 0), a3, voffA);
;             PG8_WAIT_V(8); PG8_WAIT_L(0); PG8_BAR; PG8_MMA(1, 0, At, B0); PG8_MMA(1, 1, At, B1); PG8_BAR; PG8_SCHED;
;         }
	s_setprio 1
	s_waitcnt lgkmcnt(0)
	v_mfma_i32_16x16x64_i8 v[142:145], v[66:69], v[188:191], v[142:145]
	v_mfma_i32_16x16x64_i8 v[138:141], v[74:77], v[188:191], v[138:141]
	v_mfma_i32_16x16x64_i8 v[126:129], v[66:69], v[196:199], v[126:129]
	v_mfma_i32_16x16x64_i8 v[122:125], v[74:77], v[196:199], v[122:125]
	v_mfma_i32_16x16x64_i8 v[110:113], v[66:69], v[204:207], v[110:113]
	v_mfma_i32_16x16x64_i8 v[106:109], v[74:77], v[204:207], v[106:109]
	v_mfma_i32_16x16x64_i8 v[94:97], v[66:69], v[212:215], v[94:97]
	v_mfma_i32_16x16x64_i8 v[90:93], v[74:77], v[212:215], v[90:93]
	v_mfma_i32_16x16x64_i8 v[142:145], v[70:73], v[192:195], v[142:145]
	v_mfma_i32_16x16x64_i8 v[138:141], v[78:81], v[192:195], v[138:141]
	v_mfma_i32_16x16x64_i8 v[126:129], v[70:73], v[200:203], v[126:129]
	v_mfma_i32_16x16x64_i8 v[122:125], v[78:81], v[200:203], v[122:125]
	v_mfma_i32_16x16x64_i8 v[110:113], v[70:73], v[208:211], v[110:113]
	v_mfma_i32_16x16x64_i8 v[106:109], v[78:81], v[208:211], v[106:109]
	v_mfma_i32_16x16x64_i8 v[94:97], v[70:73], v[216:219], v[94:97]
	v_mfma_i32_16x16x64_i8 v[90:93], v[78:81], v[216:219], v[90:93]
	s_setprio 0
	s_setprio 1
	v_mfma_i32_16x16x64_i8 v[134:137], v[146:149], v[188:191], v[134:137]
	v_mfma_i32_16x16x64_i8 v[130:133], v[174:177], v[188:191], v[130:133]
	v_mfma_i32_16x16x64_i8 v[118:121], v[146:149], v[196:199], v[118:121]
	v_mfma_i32_16x16x64_i8 v[114:117], v[174:177], v[196:199], v[114:117]
	v_mfma_i32_16x16x64_i8 v[102:105], v[146:149], v[204:207], v[102:105]
	v_mfma_i32_16x16x64_i8 v[98:101], v[174:177], v[204:207], v[98:101]
	v_mfma_i32_16x16x64_i8 v[86:89], v[146:149], v[212:215], v[86:89]
	v_mfma_i32_16x16x64_i8 v[82:85], v[174:177], v[212:215], v[82:85]
	v_mfma_i32_16x16x64_i8 v[134:137], v[150:153], v[192:195], v[134:137]
	v_mfma_i32_16x16x64_i8 v[130:133], v[184:187], v[192:195], v[130:133]
	v_mfma_i32_16x16x64_i8 v[118:121], v[150:153], v[200:203], v[118:121]
	v_mfma_i32_16x16x64_i8 v[114:117], v[184:187], v[200:203], v[114:117]
	v_mfma_i32_16x16x64_i8 v[102:105], v[150:153], v[208:211], v[102:105]
	v_mfma_i32_16x16x64_i8 v[98:101], v[184:187], v[208:211], v[98:101]
	v_mfma_i32_16x16x64_i8 v[86:89], v[150:153], v[216:219], v[86:89]
	v_mfma_i32_16x16x64_i8 v[82:85], v[184:187], v[216:219], v[82:85]
	s_setprio 0
	s_barrier
	s_add_u32 s24, s22, 0x8000
	s_addc_u32 s25, s23, 0
	s_add_i32 s50, s50, s30
	v_lshl_add_u64 v[220:221], s[24:25], 0, v[158:159]
	s_mov_b32 m0, s50
	ds_read_b128 v[188:191], v182 offset:49152
	ds_read_b128 v[192:195], v182 offset:50176
	ds_read_b128 v[196:199], v182 offset:51200
	ds_read_b128 v[200:203], v182 offset:52224
	ds_read_b128 v[204:207], v182 offset:53248
	ds_read_b128 v[208:211], v182 offset:54272
	ds_read_b128 v[212:215], v182 offset:55296
	ds_read_b128 v[216:219], v182 offset:56320
	global_load_lds_dwordx4 v[220:221], off
	s_add_i32 m0, s50, 0x2000
	s_add_u32 s22, s22, 0xc000
	v_lshl_add_u64 v[220:221], s[24:25], 0, v[162:163]
	s_addc_u32 s23, s23, 0
	s_add_i32 s24, s51, s30
	global_load_lds_dwordx4 v[220:221], off
	v_lshl_add_u64 v[220:221], s[22:23], 0, v[158:159]
	s_mov_b32 m0, s24
	s_nop 0
	global_load_lds_dwordx4 v[220:221], off
	v_lshl_add_u64 v[220:221], s[22:23], 0, v[162:163]
	s_add_i32 m0, s24, 0x2000
	s_nop 0
	global_load_lds_dwordx4 v[220:221], off
	s_waitcnt vmcnt(6)
	s_waitcnt lgkmcnt(0)
	s_barrier
	s_setprio 1
	s_waitcnt lgkmcnt(0)
	v_mfma_i32_16x16x64_i8 v[62:65], v[66:69], v[188:191], v[62:65]
	v_mfma_i32_16x16x64_i8 v[58:61], v[74:77], v[188:191], v[58:61]
	v_mfma_i32_16x16x64_i8 v[46:49], v[66:69], v[196:199], v[46:49]
	v_mfma_i32_16x16x64_i8 v[42:45], v[74:77], v[196:199], v[42:45]
	v_mfma_i32_16x16x64_i8 v[30:33], v[66:69], v[204:207], v[30:33]
	v_mfma_i32_16x16x64_i8 v[26:29], v[74:77], v[204:207], v[26:29]
	v_mfma_i32_16x16x64_i8 v[14:17], v[66:69], v[212:215], v[14:17]
	v_mfma_i32_16x16x64_i8 v[10:13], v[74:77], v[212:215], v[10:13]
	v_mfma_i32_16x16x64_i8 v[62:65], v[70:73], v[192:195], v[62:65]
	v_mfma_i32_16x16x64_i8 v[58:61], v[78:81], v[192:195], v[58:61]
	v_mfma_i32_16x16x64_i8 v[46:49], v[70:73], v[200:203], v[46:49]
	v_mfma_i32_16x16x64_i8 v[42:45], v[78:81], v[200:203], v[42:45]
	v_mfma_i32_16x16x64_i8 v[30:33], v[70:73], v[208:211], v[30:33]
	v_mfma_i32_16x16x64_i8 v[26:29], v[78:81], v[208:211], v[26:29]
	v_mfma_i32_16x16x64_i8 v[14:17], v[70:73], v[216:219], v[14:17]
	v_mfma_i32_16x16x64_i8 v[10:13], v[78:81], v[216:219], v[10:13]
	s_setprio 0
	s_setprio 1
	v_mfma_i32_16x16x64_i8 v[54:57], v[146:149], v[188:191], v[54:57]
	v_mfma_i32_16x16x64_i8 v[50:53], v[174:177], v[188:191], v[50:53]
	v_mfma_i32_16x16x64_i8 v[38:41], v[146:149], v[196:199], v[38:41]
	v_mfma_i32_16x16x64_i8 v[34:37], v[174:177], v[196:199], v[34:37]
	v_mfma_i32_16x16x64_i8 v[22:25], v[146:149], v[204:207], v[22:25]
	v_mfma_i32_16x16x64_i8 v[18:21], v[174:177], v[204:207], v[18:21]
	v_mfma_i32_16x16x64_i8 v[6:9], v[146:149], v[212:215], v[6:9]
	v_mfma_i32_16x16x64_i8 v[2:5], v[174:177], v[212:215], v[2:5]
	v_mfma_i32_16x16x64_i8 v[54:57], v[150:153], v[192:195], v[54:57]
	v_mfma_i32_16x16x64_i8 v[50:53], v[184:187], v[192:195], v[50:53]
	v_mfma_i32_16x16x64_i8 v[38:41], v[150:153], v[200:203], v[38:41]
	v_mfma_i32_16x16x64_i8 v[34:37], v[184:187], v[200:203], v[34:37]
	v_mfma_i32_16x16x64_i8 v[22:25], v[150:153], v[208:211], v[22:25]
	v_mfma_i32_16x16x64_i8 v[18:21], v[184:187], v[208:211], v[18:21]
	v_mfma_i32_16x16x64_i8 v[6:9], v[150:153], v[216:219], v[6:9]
	v_mfma_i32_16x16x64_i8 v[2:5], v[184:187], v[216:219], v[2:5]
	s_setprio 0
	s_barrier
	s_add_i32 s49, s49, 2
	s_add_u32 s18, s18, 0x10000
	s_addc_u32 s19, s19, 0
	s_add_u32 s47, s47, 0x10000
	s_addc_u32 s48, s48, 0
	s_cmpk_gt_u32 s49, 0x53
	s_cbranch_scc0 .LBB0_1393
	s_and_b64 vcc, exec, s[14:15]
	s_cbranch_vccz .LBB0_1396
	s_barrier

; #define PG8_STAGE(bufoff, gbase, voff) do { _Pragma("unroll") for (int _i = 0; _i < 2; ++_i) \
;         __builtin_amdgcn_global_load_lds((const unsigned*)((const char*)(gbase) + (voff)[_i]), (LAS unsigned*)(lds + (bufoff) + ldsw + _i * 8192), 16, 0, 0); } while (0)
; #define PG8_LDA(dst, b, h) do { _Pragma("unroll") for (int m = 0; m < 4; ++m) _Pragma("unroll") for (int k = 0; k < 2; ++k) dst[m][k] = *(const LAS bf16x8*)(lds + PG8_SA(b, h) + aoff + m * 2048 + k * 1024); } while (0)
; #define PG8_LDB(dst, b, h) do { _Pragma("unroll") for (int n = 0; n < 2; ++n) _Pragma("unroll") for (int k = 0; k < 2; ++k) dst[n][k] = *(const LAS bf16x8*)(lds + PG8_SB(b, h) + boff + n * 2048 + k * 1024); } while (0)
; #define PG8_WAIT_V(n) asm volatile("s_waitcnt vmcnt(" #n ")" ::: "memory")
; #define PG8_WAIT_L(n) asm volatile("s_waitcnt lgkmcnt(" #n ")" ::: "memory")
; #define PG8_BAR __builtin_amdgcn_s_barrier()
; #define PG8_SCHED __builtin_amdgcn_sched_barrier(0)
; template <class Epi, class Sched, bool I8 = false>
; __device__ __forceinline__ void gemm_phase(LAS unsigned char* lds, const Gemm g, const Sched& S, const Epi& E) {
;     ...
;         for (int t = 0; t < nt; t += 2) {
;             const bool last = (t == nt - 2);
;             const char* a1 = cA + (size_t)(t + 1) * kstep;
;             const char* a2 = last ? nA : cA + (size_t)(t + 2) * kstep; const char* b2 = last ? nB : cB + (size_t)(t + 2) * kstep;
;             const char* a3 = a2 + kstep; const char* b3 = b2 + kstep;
;             PG8_LDB(B0, 0, 0); PG8_LDB(B1, 0, 1); PG8_SCHED; PG8_LDA(At, 0, 0); PG8_STAGE(PG8_SA(1, 1), a1 + hstepA, voffA);
;             PG8_WAIT_V(8); PG8_WAIT_L(0); PG8_BAR; PG8_MMA(0, 0, At, B0); PG8_MMA(0, 1, At, B1); PG8_BAR; PG8_SCHED;
;             PG8_LDA(At, 0, 1); PG8_STAGE(PG8_SB(0, 0), b2, voffB); PG8_STAGE(PG8_SB(0, 1), b2 + hstepB, voffB); PG8_STAGE(PG8_SA(0, 0), a2, voffA);
;             PG8_WAIT_V(8); PG8_WAIT_L(0); PG8_BAR; PG8_MMA(1, 0, At, B0); PG8_MMA(1, 1, At, B1); PG8_BAR; PG8_SCHED;
.LBB0_1482:
	ds_read_b128 v[152:155], v182
	ds_read_b128 v[156:159], v182 offset:1024
	ds_read_b128 v[160:163], v182 offset:2048
	ds_read_b128 v[164:167], v182 offset:3072
	ds_read_b128 v[168:171], v183
	ds_read_b128 v[172:175], v183 offset:1024
	ds_read_b128 v[176:179], v183 offset:2048
	ds_read_b128 v[186:189], v183 offset:3072
	s_add_u32 s38, s8, 0x4000
	s_addc_u32 s39, s9, 0
	s_cmp_eq_u32 s47, 60
	s_cselect_b32 s42, s31, s38
	s_cselect_b32 s43, s7, s39
	s_cselect_b32 s40, s44, s45
	s_cselect_b32 s41, s29, s46
	s_add_u32 s38, s42, 0x8000
	s_addc_u32 s39, s43, 0
	s_sub_u32 s98, s8, 0x4000
	s_subb_u32 s99, s9, 0
	v_lshl_add_u64 v[222:223], s[98:99], 0, v[130:131]
	s_mov_b32 m0, s58
	s_nop 0
	global_load_lds_dwordx4 v[222:223], off
	v_lshl_add_u64 v[222:223], s[98:99], 0, v[134:135]
	s_mov_b32 m0, s59
	s_nop 0
	global_load_lds_dwordx4 v[222:223], off
	v_lshl_add_u64 v[222:223], s[8:9], 0, v[144:145]
	s_add_i32 m0, s33, 0xc000
	ds_read_b128 v[190:193], v184
	ds_read_b128 v[194:197], v184 offset:1024
	ds_read_b128 v[198:201], v184 offset:2048
	ds_read_b128 v[202:205], v184 offset:3072
	ds_read_b128 v[206:209], v184 offset:4096
	ds_read_b128 v[210:213], v184 offset:5120
	ds_read_b128 v[214:217], v184 offset:6144
	ds_read_b128 v[218:221], v184 offset:7168
	global_load_lds_dwordx4 v[222:223], off
	v_lshl_add_u64 v[222:223], s[8:9], 0, v[146:147]
	s_add_i32 m0, s33, 0xe000
	s_nop 0
	global_load_lds_dwordx4 v[222:223], off
	s_waitcnt vmcnt(8)
	s_waitcnt lgkmcnt(0)
	s_barrier
	s_setprio 1
	s_waitcnt lgkmcnt(0)
	v_mfma_f32_16x16x32_bf16 v[126:129], v[152:155], v[190:193], v[126:129]
	v_mfma_f32_16x16x32_bf16 v[122:125], v[160:163], v[190:193], v[122:125]
	v_mfma_f32_16x16x32_bf16 v[110:113], v[152:155], v[198:201], v[110:113]
	v_mfma_f32_16x16x32_bf16 v[106:109], v[160:163], v[198:201], v[106:109]
	v_mfma_f32_16x16x32_bf16 v[94:97], v[152:155], v[206:209], v[94:97]
	v_mfma_f32_16x16x32_bf16 v[90:93], v[160:163], v[206:209], v[90:93]
	v_mfma_f32_16x16x32_bf16 v[78:81], v[152:155], v[214:217], v[78:81]
	v_mfma_f32_16x16x32_bf16 v[74:77], v[160:163], v[214:217], v[74:77]
	v_mfma_f32_16x16x32_bf16 v[126:129], v[156:159], v[194:197], v[126:129]
	v_mfma_f32_16x16x32_bf16 v[122:125], v[164:167], v[194:197], v[122:125]
	v_mfma_f32_16x16x32_bf16 v[110:113], v[156:159], v[202:205], v[110:113]
	v_mfma_f32_16x16x32_bf16 v[106:109], v[164:167], v[202:205], v[106:109]
	v_mfma_f32_16x16x32_bf16 v[94:97], v[156:159], v[210:213], v[94:97]
	v_mfma_f32_16x16x32_bf16 v[90:93], v[164:167], v[210:213], v[90:93]
	v_mfma_f32_16x16x32_bf16 v[78:81], v[156:159], v[218:221], v[78:81]
	v_mfma_f32_16x16x32_bf16 v[74:77], v[164:167], v[218:221], v[74:77]
	s_setprio 0
	s_setprio 1
	v_mfma_f32_16x16x32_bf16 v[118:121], v[168:171], v[190:193], v[118:121]
	v_mfma_f32_16x16x32_bf16 v[114:117], v[176:179], v[190:193], v[114:117]
	v_mfma_f32_16x16x32_bf16 v[102:105], v[168:171], v[198:201], v[102:105]
	v_mfma_f32_16x16x32_bf16 v[98:101], v[176:179], v[198:201], v[98:101]
	v_mfma_f32_16x16x32_bf16 v[86:89], v[168:171], v[206:209], v[86:89]
	v_mfma_f32_16x16x32_bf16 v[82:85], v[176:179], v[206:209], v[82:85]
	v_mfma_f32_16x16x32_bf16 v[70:73], v[168:171], v[214:217], v[70:73]
	v_mfma_f32_16x16x32_bf16 v[66:69], v[176:179], v[214:217], v[66:69]
	v_mfma_f32_16x16x32_bf16 v[118:121], v[172:175], v[194:197], v[118:121]
	v_mfma_f32_16x16x32_bf16 v[114:117], v[186:189], v[194:197], v[114:117]
	v_mfma_f32_16x16x32_bf16 v[102:105], v[172:175], v[202:205], v[102:105]
	v_mfma_f32_16x16x32_bf16 v[98:101], v[186:189], v[202:205], v[98:101]
	v_mfma_f32_16x16x32_bf16 v[86:89], v[172:175], v[210:213], v[86:89]
	v_mfma_f32_16x16x32_bf16 v[82:85], v[186:189], v[210:213], v[82:85]
	v_mfma_f32_16x16x32_bf16 v[70:73], v[172:175], v[218:221], v[70:73]
	v_mfma_f32_16x16x32_bf16 v[66:69], v[186:189], v[218:221], v[66:69]
	s_setprio 0
	s_barrier
	s_add_i32 s48, s63, s25
	v_lshl_add_u64 v[222:223], s[40:41], 0, v[132:133]
	s_mov_b32 m0, s48
	ds_read_b128 v[190:193], v184 offset:16384
	ds_read_b128 v[194:197], v184 offset:17408
	ds_read_b128 v[198:201], v184 offset:18432
	ds_read_b128 v[202:205], v184 offset:19456
	ds_read_b128 v[206:209], v184 offset:20480
	ds_read_b128 v[210:213], v184 offset:21504
	ds_read_b128 v[214:217], v184 offset:22528
	ds_read_b128 v[218:221], v184 offset:23552
	global_load_lds_dwordx4 v[222:223], off
	s_add_i32 m0, s48, 0x2000
	s_add_u32 s48, s40, 0x4000
	v_lshl_add_u64 v[222:223], s[40:41], 0, v[136:137]
	s_addc_u32 s49, s41, 0
	s_add_i32 s50, s64, s25
	global_load_lds_dwordx4 v[222:223], off
	v_lshl_add_u64 v[222:223], s[48:49], 0, v[132:133]
	s_mov_b32 m0, s50
	s_nop 0
	global_load_lds_dwordx4 v[222:223], off
	v_lshl_add_u64 v[222:223], s[48:49], 0, v[136:137]
	s_add_i32 m0, s50, 0x2000
	s_nop 0
	global_load_lds_dwordx4 v[222:223], off
	s_waitcnt vmcnt(6)
	s_waitcnt lgkmcnt(0)
	s_barrier
; #define PG8_STAGE(bufoff, gbase, voff) do { _Pragma("unroll") for (int _i = 0; _i < 2; ++_i) \
;         __builtin_amdgcn_global_load_lds((const unsigned*)((const char*)(gbase) + (voff)[_i]), (LAS unsigned*)(lds + (bufoff) + ldsw + _i * 8192), 16, 0, 0); } while (0)
; #define PG8_LDA(dst, b, h) do { _Pragma("unroll") for (int m = 0; m < 4; ++m) _Pragma("unroll") for (int k = 0; k < 2; ++k) dst[m][k] = *(const LAS bf16x8*)(lds + PG8_SA(b, h) + aoff + m * 2048 + k * 1024); } while (0)
; #define PG8_LDB(dst, b, h) do { _Pragma("unroll") for (int n = 0; n < 2; ++n) _Pragma("unroll") for (int k = 0; k < 2; ++k) dst[n][k] = *(const LAS bf16x8*)(lds + PG8_SB(b, h) + boff + n * 2048 + k * 1024); } while (0)
; #define PG8_WAIT_V(n) asm volatile("s_waitcnt vmcnt(" #n ")" ::: "memory")
; #define PG8_WAIT_L(n) asm volatile("s_waitcnt lgkmcnt(" #n ")" ::: "memory")
; #define PG8_BAR __builtin_amdgcn_s_barrier()
; #define PG8_SCHED __builtin_amdgcn_sched_barrier(0)
; template <class Epi, class Sched, bool I8 = false>
; __device__ __forceinline__ void gemm_phase(LAS unsigned char* lds, const Gemm g, const Sched& S, const Epi& E) {
;     ...
;             PG8_WAIT_V(8); PG8_WAIT_L(0); PG8_BAR; PG8_MMA(1, 0, At, B0); PG8_MMA(1, 1, At, B1); PG8_BAR; PG8_SCHED;
;             PG8_LDB(B0, 1, 0); PG8_LDB(B1, 1, 1); PG8_SCHED; PG8_LDA(At, 1, 0); PG8_STAGE(PG8_SA(0, 1), a2 + hstepA, voffA);
;             PG8_WAIT_V(8); PG8_WAIT_L(0); PG8_BAR; PG8_MMA(0, 0, At, B0); PG8_MMA(0, 1, At, B1); PG8_BAR; PG8_SCHED;
	s_setprio 1
	s_waitcnt lgkmcnt(0)
	v_mfma_f32_16x16x32_bf16 v[62:65], v[152:155], v[190:193], v[62:65]
	v_mfma_f32_16x16x32_bf16 v[58:61], v[160:163], v[190:193], v[58:61]
	v_mfma_f32_16x16x32_bf16 v[46:49], v[152:155], v[198:201], v[46:49]
	v_mfma_f32_16x16x32_bf16 v[42:45], v[160:163], v[198:201], v[42:45]
	v_mfma_f32_16x16x32_bf16 v[30:33], v[152:155], v[206:209], v[30:33]
	v_mfma_f32_16x16x32_bf16 v[26:29], v[160:163], v[206:209], v[26:29]
	v_mfma_f32_16x16x32_bf16 v[14:17], v[152:155], v[214:217], v[14:17]
	v_mfma_f32_16x16x32_bf16 v[10:13], v[160:163], v[214:217], v[10:13]
	v_mfma_f32_16x16x32_bf16 v[62:65], v[156:159], v[194:197], v[62:65]
	v_mfma_f32_16x16x32_bf16 v[58:61], v[164:167], v[194:197], v[58:61]
	v_mfma_f32_16x16x32_bf16 v[46:49], v[156:159], v[202:205], v[46:49]
	v_mfma_f32_16x16x32_bf16 v[42:45], v[164:167], v[202:205], v[42:45]
	v_mfma_f32_16x16x32_bf16 v[30:33], v[156:159], v[210:213], v[30:33]
	v_mfma_f32_16x16x32_bf16 v[26:29], v[164:167], v[210:213], v[26:29]
	v_mfma_f32_16x16x32_bf16 v[14:17], v[156:159], v[218:221], v[14:17]
	v_mfma_f32_16x16x32_bf16 v[10:13], v[164:167], v[218:221], v[10:13]
	s_setprio 0
	s_setprio 1
	v_mfma_f32_16x16x32_bf16 v[54:57], v[168:171], v[190:193], v[54:57]
	v_mfma_f32_16x16x32_bf16 v[50:53], v[176:179], v[190:193], v[50:53]
	v_mfma_f32_16x16x32_bf16 v[38:41], v[168:171], v[198:201], v[38:41]
	v_mfma_f32_16x16x32_bf16 v[34:37], v[176:179], v[198:201], v[34:37]
	v_mfma_f32_16x16x32_bf16 v[22:25], v[168:171], v[206:209], v[22:25]
	v_mfma_f32_16x16x32_bf16 v[18:21], v[176:179], v[206:209], v[18:21]
	v_mfma_f32_16x16x32_bf16 v[6:9], v[168:171], v[214:217], v[6:9]
	v_mfma_f32_16x16x32_bf16 v[2:5], v[176:179], v[214:217], v[2:5]
	v_mfma_f32_16x16x32_bf16 v[54:57], v[172:175], v[194:197], v[54:57]
	v_mfma_f32_16x16x32_bf16 v[50:53], v[186:189], v[194:197], v[50:53]
	v_mfma_f32_16x16x32_bf16 v[38:41], v[172:175], v[202:205], v[38:41]
	v_mfma_f32_16x16x32_bf16 v[34:37], v[186:189], v[202:205], v[34:37]
	v_mfma_f32_16x16x32_bf16 v[22:25], v[172:175], v[210:213], v[22:25]
	v_mfma_f32_16x16x32_bf16 v[18:21], v[186:189], v[210:213], v[18:21]
	v_mfma_f32_16x16x32_bf16 v[6:9], v[172:175], v[218:221], v[6:9]
	v_mfma_f32_16x16x32_bf16 v[2:5], v[186:189], v[218:221], v[2:5]
	s_setprio 0
	s_barrier
	s_add_i32 s48, 0, 0x18000
	v_add_u32_e32 v138, s48, v181
	s_add_i32 s49, 0, 0x1c000
	ds_read_b128 v[152:155], v138
	ds_read_b128 v[156:159], v138 offset:1024
	ds_read_b128 v[160:163], v138 offset:2048
	ds_read_b128 v[164:167], v138 offset:3072
	v_add_u32_e32 v138, s49, v181
	ds_read_b128 v[168:171], v138
	ds_read_b128 v[172:175], v138 offset:1024
	ds_read_b128 v[176:179], v138 offset:2048
	ds_read_b128 v[186:189], v138 offset:3072
	v_lshl_add_u64 v[222:223], s[42:43], 0, v[130:131]
	s_mov_b32 m0, s33
	s_nop 0
	global_load_lds_dwordx4 v[222:223], off
	v_lshl_add_u64 v[222:223], s[42:43], 0, v[134:135]
	s_mov_b32 m0, s52
	s_nop 0
	global_load_lds_dwordx4 v[222:223], off
	s_add_u32 s42, s42, 0x4000
	s_addc_u32 s43, s43, 0
	s_mov_b32 m0, s53
	v_lshl_add_u64 v[222:223], s[42:43], 0, v[130:131]
	ds_read_b128 v[190:193], v184 offset:32768
	ds_read_b128 v[194:197], v184 offset:33792
	ds_read_b128 v[198:201], v184 offset:34816
	ds_read_b128 v[202:205], v184 offset:35840
	ds_read_b128 v[206:209], v184 offset:36864
	ds_read_b128 v[210:213], v184 offset:37888
	ds_read_b128 v[214:217], v184 offset:38912
	ds_read_b128 v[218:221], v184 offset:39936
	global_load_lds_dwordx4 v[222:223], off
	v_lshl_add_u64 v[222:223], s[42:43], 0, v[134:135]
	s_mov_b32 m0, s54
	s_nop 0
	global_load_lds_dwordx4 v[222:223], off
	s_waitcnt vmcnt(8)
	s_waitcnt lgkmcnt(0)
	s_barrier
; #define PG8_STAGE(bufoff, gbase, voff) do { _Pragma("unroll") for (int _i = 0; _i < 2; ++_i) \
;         __builtin_amdgcn_global_load_lds((const unsigned*)((const char*)(gbase) + (voff)[_i]), (LAS unsigned*)(lds + (bufoff) + ldsw + _i * 8192), 16, 0, 0); } while (0)
; #define PG8_LDA(dst, b, h) do { _Pragma("unroll") for (int m = 0; m < 4; ++m) _Pragma("unroll") for (int k = 0; k < 2; ++k) dst[m][k] = *(const LAS bf16x8*)(lds + PG8_SA(b, h) + aoff + m * 2048 + k * 1024); } while (0)
; #define PG8_WAIT_V(n) asm volatile("s_waitcnt vmcnt(" #n ")" ::: "memory")
; #define PG8_WAIT_L(n) asm volatile("s_waitcnt lgkmcnt(" #n ")" ::: "memory")
; #define PG8_BAR __builtin_amdgcn_s_barrier()
; #define PG8_SCHED __builtin_amdgcn_sched_barrier(0)
; template <class Epi, class Sched, bool I8 = false>
; __device__ __forceinline__ void gemm_phase(LAS unsigned char* lds, const Gemm g, const Sched& S, const Epi& E) {
;     ...
;             PG8_WAIT_V(8); PG8_WAIT_L(0); PG8_BAR; PG8_MMA(0, 0, At, B0); PG8_MMA(0, 1, At, B1); PG8_BAR; PG8_SCHED;
;             PG8_LDA(At, 1, 1); PG8_STAGE(PG8_SB(1, 0), b3, voffB); PG8_STAGE(PG8_SB(1, 1), b3 + hstepB, voffB); PG8_STAGE(PG8_SA(1, 0), a3, voffA);
;             PG8_WAIT_V(8); PG8_WAIT_L(0); PG8_BAR; PG8_MMA(1, 0, At, B0); PG8_MMA(1, 1, At, B1); PG8_BAR; PG8_SCHED;
;         }
	s_setprio 1
	s_waitcnt lgkmcnt(0)
	v_mfma_f32_16x16x32_bf16 v[126:129], v[152:155], v[190:193], v[126:129]
	v_mfma_f32_16x16x32_bf16 v[122:125], v[160:163], v[190:193], v[122:125]
	v_mfma_f32_16x16x32_bf16 v[110:113], v[152:155], v[198:201], v[110:113]
	v_mfma_f32_16x16x32_bf16 v[106:109], v[160:163], v[198:201], v[106:109]
	v_mfma_f32_16x16x32_bf16 v[94:97], v[152:155], v[206:209], v[94:97]
	v_mfma_f32_16x16x32_bf16 v[90:93], v[160:163], v[206:209], v[90:93]
	v_mfma_f32_16x16x32_bf16 v[78:81], v[152:155], v[214:217], v[78:81]
	v_mfma_f32_16x16x32_bf16 v[74:77], v[160:163], v[214:217], v[74:77]
	v_mfma_f32_16x16x32_bf16 v[126:129], v[156:159], v[194:197], v[126:129]
	v_mfma_f32_16x16x32_bf16 v[122:125], v[164:167], v[194:197], v[122:125]
	v_mfma_f32_16x16x32_bf16 v[110:113], v[156:159], v[202:205], v[110:113]
	v_mfma_f32_16x16x32_bf16 v[106:109], v[164:167], v[202:205], v[106:109]
	v_mfma_f32_16x16x32_bf16 v[94:97], v[156:159], v[210:213], v[94:97]
	v_mfma_f32_16x16x32_bf16 v[90:93], v[164:167], v[210:213], v[90:93]
	v_mfma_f32_16x16x32_bf16 v[78:81], v[156:159], v[218:221], v[78:81]
	v_mfma_f32_16x16x32_bf16 v[74:77], v[164:167], v[218:221], v[74:77]
	s_setprio 0
	s_setprio 1
	v_mfma_f32_16x16x32_bf16 v[118:121], v[168:171], v[190:193], v[118:121]
	v_mfma_f32_16x16x32_bf16 v[114:117], v[176:179], v[190:193], v[114:117]
	v_mfma_f32_16x16x32_bf16 v[102:105], v[168:171], v[198:201], v[102:105]
	v_mfma_f32_16x16x32_bf16 v[98:101], v[176:179], v[198:201], v[98:101]
	v_mfma_f32_16x16x32_bf16 v[86:89], v[168:171], v[206:209], v[86:89]
	v_mfma_f32_16x16x32_bf16 v[82:85], v[176:179], v[206:209], v[82:85]
	v_mfma_f32_16x16x32_bf16 v[70:73], v[168:171], v[214:217], v[70:73]
	v_mfma_f32_16x16x32_bf16 v[66:69], v[176:179], v[214:217], v[66:69]
	v_mfma_f32_16x16x32_bf16 v[118:121], v[172:175], v[194:197], v[118:121]
	v_mfma_f32_16x16x32_bf16 v[114:117], v[186:189], v[194:197], v[114:117]
	v_mfma_f32_16x16x32_bf16 v[102:105], v[172:175], v[202:205], v[102:105]
	v_mfma_f32_16x16x32_bf16 v[98:101], v[186:189], v[202:205], v[98:101]
	v_mfma_f32_16x16x32_bf16 v[86:89], v[172:175], v[210:213], v[86:89]
	v_mfma_f32_16x16x32_bf16 v[82:85], v[186:189], v[210:213], v[82:85]
	v_mfma_f32_16x16x32_bf16 v[70:73], v[172:175], v[218:221], v[70:73]
	v_mfma_f32_16x16x32_bf16 v[66:69], v[186:189], v[218:221], v[66:69]
	s_setprio 0
	s_barrier
	s_add_u32 s42, s40, 0x8000
	s_addc_u32 s43, s41, 0
	s_add_i32 s48, s48, s25
	v_lshl_add_u64 v[222:223], s[42:43], 0, v[132:133]
	s_mov_b32 m0, s48
	ds_read_b128 v[190:193], v184 offset:49152
	ds_read_b128 v[194:197], v184 offset:50176
	ds_read_b128 v[198:201], v184 offset:51200
	ds_read_b128 v[202:205], v184 offset:52224
	ds_read_b128 v[206:209], v184 offset:53248
	ds_read_b128 v[210:213], v184 offset:54272
	ds_read_b128 v[214:217], v184 offset:55296
	ds_read_b128 v[218:221], v184 offset:56320
	global_load_lds_dwordx4 v[222:223], off
	s_add_i32 m0, s48, 0x2000
	s_add_u32 s40, s40, 0xc000
	v_lshl_add_u64 v[222:223], s[42:43], 0, v[136:137]
	s_addc_u32 s41, s41, 0
	s_add_i32 s42, s49, s25
	global_load_lds_dwordx4 v[222:223], off
	v_lshl_add_u64 v[222:223], s[40:41], 0, v[132:133]
	s_mov_b32 m0, s42
	s_nop 0
	global_load_lds_dwordx4 v[222:223], off
	v_lshl_add_u64 v[222:223], s[40:41], 0, v[136:137]
	s_add_i32 m0, s42, 0x2000
	s_nop 0
	global_load_lds_dwordx4 v[222:223], off
	s_waitcnt vmcnt(6)
	s_waitcnt lgkmcnt(0)
	s_barrier
	s_setprio 1
	s_waitcnt lgkmcnt(0)
	v_mfma_f32_16x16x32_bf16 v[62:65], v[152:155], v[190:193], v[62:65]
	v_mfma_f32_16x16x32_bf16 v[58:61], v[160:163], v[190:193], v[58:61]
	v_mfma_f32_16x16x32_bf16 v[46:49], v[152:155], v[198:201], v[46:49]
	v_mfma_f32_16x16x32_bf16 v[42:45], v[160:163], v[198:201], v[42:45]
	v_mfma_f32_16x16x32_bf16 v[30:33], v[152:155], v[206:209], v[30:33]
	v_mfma_f32_16x16x32_bf16 v[26:29], v[160:163], v[206:209], v[26:29]
	v_mfma_f32_16x16x32_bf16 v[14:17], v[152:155], v[214:217], v[14:17]
	v_mfma_f32_16x16x32_bf16 v[10:13], v[160:163], v[214:217], v[10:13]
	v_mfma_f32_16x16x32_bf16 v[62:65], v[156:159], v[194:197], v[62:65]
	v_mfma_f32_16x16x32_bf16 v[58:61], v[164:167], v[194:197], v[58:61]
	v_mfma_f32_16x16x32_bf16 v[46:49], v[156:159], v[202:205], v[46:49]
	v_mfma_f32_16x16x32_bf16 v[42:45], v[164:167], v[202:205], v[42:45]
	v_mfma_f32_16x16x32_bf16 v[30:33], v[156:159], v[210:213], v[30:33]
	v_mfma_f32_16x16x32_bf16 v[26:29], v[164:167], v[210:213], v[26:29]
	v_mfma_f32_16x16x32_bf16 v[14:17], v[156:159], v[218:221], v[14:17]
	v_mfma_f32_16x16x32_bf16 v[10:13], v[164:167], v[218:221], v[10:13]
	s_setprio 0
	s_setprio 1
	v_mfma_f32_16x16x32_bf16 v[54:57], v[168:171], v[190:193], v[54:57]
	v_mfma_f32_16x16x32_bf16 v[50:53], v[176:179], v[190:193], v[50:53]
	v_mfma_f32_16x16x32_bf16 v[38:41], v[168:171], v[198:201], v[38:41]
	v_mfma_f32_16x16x32_bf16 v[34:37], v[176:179], v[198:201], v[34:37]
	v_mfma_f32_16x16x32_bf16 v[22:25], v[168:171], v[206:209], v[22:25]
	v_mfma_f32_16x16x32_bf16 v[18:21], v[176:179], v[206:209], v[18:21]
	v_mfma_f32_16x16x32_bf16 v[6:9], v[168:171], v[214:217], v[6:9]
	v_mfma_f32_16x16x32_bf16 v[2:5], v[176:179], v[214:217], v[2:5]
	v_mfma_f32_16x16x32_bf16 v[54:57], v[172:175], v[194:197], v[54:57]
	v_mfma_f32_16x16x32_bf16 v[50:53], v[186:189], v[194:197], v[50:53]
	v_mfma_f32_16x16x32_bf16 v[38:41], v[172:175], v[202:205], v[38:41]
	v_mfma_f32_16x16x32_bf16 v[34:37], v[186:189], v[202:205], v[34:37]
	v_mfma_f32_16x16x32_bf16 v[22:25], v[172:175], v[210:213], v[22:25]
	v_mfma_f32_16x16x32_bf16 v[18:21], v[186:189], v[210:213], v[18:21]
	v_mfma_f32_16x16x32_bf16 v[6:9], v[172:175], v[218:221], v[6:9]
	v_mfma_f32_16x16x32_bf16 v[2:5], v[186:189], v[218:221], v[2:5]
	s_setprio 0
	s_barrier
	s_add_i32 s47, s47, 2
	s_add_u32 s8, s8, 0x10000
	s_addc_u32 s9, s9, 0
	s_add_u32 s45, s45, 0x10000
	s_addc_u32 s46, s46, 0
	s_cmp_gt_u32 s47, 61
	s_cbranch_scc0 .LBB0_1482
	s_and_b64 vcc, exec, s[20:21]
	s_cbranch_vccz .LBB0_1485
	s_barrier

; #define PG8_STAGE(bufoff, gbase, voff) do { _Pragma("unroll") for (int _i = 0; _i < 2; ++_i) \
;         __builtin_amdgcn_global_load_lds((const unsigned*)((const char*)(gbase) + (voff)[_i]), (LAS unsigned*)(lds + (bufoff) + ldsw + _i * 8192), 16, 0, 0); } while (0)
; #define PG8_LDA(dst, b, h) do { _Pragma("unroll") for (int m = 0; m < 4; ++m) _Pragma("unroll") for (int k = 0; k < 2; ++k) dst[m][k] = *(const LAS bf16x8*)(lds + PG8_SA(b, h) + aoff + m * 2048 + k * 1024); } while (0)
; #define PG8_LDB(dst, b, h) do { _Pragma("unroll") for (int n = 0; n < 2; ++n) _Pragma("unroll") for (int k = 0; k < 2; ++k) dst[n][k] = *(const LAS bf16x8*)(lds + PG8_SB(b, h) + boff + n * 2048 + k * 1024); } while (0)
; #define PG8_WAIT_V(n) asm volatile("s_waitcnt vmcnt(" #n ")" ::: "memory")
; #define PG8_WAIT_L(n) asm volatile("s_waitcnt lgkmcnt(" #n ")" ::: "memory")
; #define PG8_BAR __builtin_amdgcn_s_barrier()
; #define PG8_SCHED __builtin_amdgcn_sched_barrier(0)
; template <class Epi, class Sched, bool I8 = false>
; __device__ __forceinline__ void gemm_phase(LAS unsigned char* lds, const Gemm g, const Sched& S, const Epi& E) {
;     ...
;         for (int t = 0; t < nt; t += 2) {
;             const bool last = (t == nt - 2);
;             const char* a1 = cA + (size_t)(t + 1) * kstep;
;             const char* a2 = last ? nA : cA + (size_t)(t + 2) * kstep; const char* b2 = last ? nB : cB + (size_t)(t + 2) * kstep;
;             const char* a3 = a2 + kstep; const char* b3 = b2 + kstep;
;             PG8_LDB(B0, 0, 0); PG8_LDB(B1, 0, 1); PG8_SCHED; PG8_LDA(At, 0, 0); PG8_STAGE(PG8_SA(1, 1), a1 + hstepA, voffA);
;             PG8_WAIT_V(8); PG8_WAIT_L(0); PG8_BAR; PG8_MMA(0, 0, At, B0); PG8_MMA(0, 1, At, B1); PG8_BAR; PG8_SCHED;
;             PG8_LDA(At, 0, 1); PG8_STAGE(PG8_SB(0, 0), b2, voffB); PG8_STAGE(PG8_SB(0, 1), b2 + hstepB, voffB); PG8_STAGE(PG8_SA(0, 0), a2, voffA);
;             PG8_WAIT_V(8); PG8_WAIT_L(0); PG8_BAR; PG8_MMA(1, 0, At, B0); PG8_MMA(1, 1, At, B1); PG8_BAR; PG8_SCHED;
.LBB0_2685:
	ds_read_b128 v[130:133], v166
	ds_read_b128 v[134:137], v166 offset:1024
	ds_read_b128 v[158:161], v166 offset:2048
	ds_read_b128 v[170:173], v166 offset:3072
	ds_read_b128 v[174:177], v167
	ds_read_b128 v[178:181], v167 offset:1024
	ds_read_b128 v[182:185], v167 offset:2048
	ds_read_b128 v[186:189], v167 offset:3072
	s_add_u32 s12, s10, 0x4000
	s_addc_u32 s13, s11, 0
	s_cmp_eq_u32 s45, 4
	s_cselect_b32 s16, s40, s12
	s_cselect_b32 s17, s39, s13
	s_cselect_b32 s14, s42, s43
	s_cselect_b32 s15, s41, s44
	s_add_u32 s12, s16, 0x8000
	s_addc_u32 s13, s17, 0
	s_sub_u32 s98, s10, 0x4000
	s_subb_u32 s99, s11, 0
	v_lshl_add_u64 v[162:163], s[98:99], 0, v[144:145]
	s_mov_b32 m0, s33
	s_nop 0
	global_load_lds_dwordx4 v[162:163], off
	v_lshl_add_u64 v[162:163], s[98:99], 0, v[140:141]
	s_mov_b32 m0, s34
	s_nop 0
	global_load_lds_dwordx4 v[162:163], off
	v_lshl_add_u64 v[162:163], s[10:11], 0, v[150:151]
	s_add_i32 m0, s26, 0xc000
	ds_read_b128 v[190:193], v168
	ds_read_b128 v[194:197], v168 offset:1024
	ds_read_b128 v[198:201], v168 offset:2048
	ds_read_b128 v[202:205], v168 offset:3072
	ds_read_b128 v[206:209], v168 offset:4096
	ds_read_b128 v[210:213], v168 offset:5120
	ds_read_b128 v[214:217], v168 offset:6144
	ds_read_b128 v[218:221], v168 offset:7168
	global_load_lds_dwordx4 v[162:163], off
	v_lshl_add_u64 v[162:163], s[10:11], 0, v[152:153]
	s_add_i32 m0, s26, 0xe000
	s_nop 0
	global_load_lds_dwordx4 v[162:163], off
	s_waitcnt vmcnt(8)
	s_waitcnt lgkmcnt(0)
	s_barrier
	s_setprio 1
	s_waitcnt lgkmcnt(0)
	v_mfma_f32_16x16x32_bf16 v[126:129], v[130:133], v[190:193], v[126:129]
	v_mfma_f32_16x16x32_bf16 v[122:125], v[158:161], v[190:193], v[122:125]
	v_mfma_f32_16x16x32_bf16 v[118:121], v[130:133], v[198:201], v[118:121]
	v_mfma_f32_16x16x32_bf16 v[114:117], v[158:161], v[198:201], v[114:117]
	v_mfma_f32_16x16x32_bf16 v[110:113], v[130:133], v[206:209], v[110:113]
	v_mfma_f32_16x16x32_bf16 v[106:109], v[158:161], v[206:209], v[106:109]
	v_mfma_f32_16x16x32_bf16 v[102:105], v[130:133], v[214:217], v[102:105]
	v_mfma_f32_16x16x32_bf16 v[98:101], v[158:161], v[214:217], v[98:101]
	v_mfma_f32_16x16x32_bf16 v[126:129], v[134:137], v[194:197], v[126:129]
	v_mfma_f32_16x16x32_bf16 v[122:125], v[170:173], v[194:197], v[122:125]
	v_mfma_f32_16x16x32_bf16 v[118:121], v[134:137], v[202:205], v[118:121]
	v_mfma_f32_16x16x32_bf16 v[114:117], v[170:173], v[202:205], v[114:117]
	v_mfma_f32_16x16x32_bf16 v[110:113], v[134:137], v[210:213], v[110:113]
	v_mfma_f32_16x16x32_bf16 v[106:109], v[170:173], v[210:213], v[106:109]
	v_mfma_f32_16x16x32_bf16 v[102:105], v[134:137], v[218:221], v[102:105]
	v_mfma_f32_16x16x32_bf16 v[98:101], v[170:173], v[218:221], v[98:101]
	s_setprio 0
	s_setprio 1
	v_mfma_f32_16x16x32_bf16 v[62:65], v[174:177], v[190:193], v[62:65]
	v_mfma_f32_16x16x32_bf16 v[58:61], v[182:185], v[190:193], v[58:61]
	v_mfma_f32_16x16x32_bf16 v[54:57], v[174:177], v[198:201], v[54:57]
	v_mfma_f32_16x16x32_bf16 v[50:53], v[182:185], v[198:201], v[50:53]
	v_mfma_f32_16x16x32_bf16 v[46:49], v[174:177], v[206:209], v[46:49]
	v_mfma_f32_16x16x32_bf16 v[42:45], v[182:185], v[206:209], v[42:45]
	v_mfma_f32_16x16x32_bf16 v[38:41], v[174:177], v[214:217], v[38:41]
	v_mfma_f32_16x16x32_bf16 v[34:37], v[182:185], v[214:217], v[34:37]
	v_mfma_f32_16x16x32_bf16 v[62:65], v[178:181], v[194:197], v[62:65]
	v_mfma_f32_16x16x32_bf16 v[58:61], v[186:189], v[194:197], v[58:61]
	v_mfma_f32_16x16x32_bf16 v[54:57], v[178:181], v[202:205], v[54:57]
	v_mfma_f32_16x16x32_bf16 v[50:53], v[186:189], v[202:205], v[50:53]
	v_mfma_f32_16x16x32_bf16 v[46:49], v[178:181], v[210:213], v[46:49]
	v_mfma_f32_16x16x32_bf16 v[42:45], v[186:189], v[210:213], v[42:45]
	v_mfma_f32_16x16x32_bf16 v[38:41], v[178:181], v[218:221], v[38:41]
	v_mfma_f32_16x16x32_bf16 v[34:37], v[186:189], v[218:221], v[34:37]
	s_setprio 0
	s_barrier
	s_add_i32 s46, s62, s22
	v_lshl_add_u64 v[162:163], s[14:15], 0, v[142:143]
	s_mov_b32 m0, s46
	ds_read_b128 v[190:193], v168 offset:16384
	ds_read_b128 v[194:197], v168 offset:17408
	ds_read_b128 v[198:201], v168 offset:18432
	ds_read_b128 v[202:205], v168 offset:19456
	ds_read_b128 v[206:209], v168 offset:20480
	ds_read_b128 v[210:213], v168 offset:21504
	ds_read_b128 v[214:217], v168 offset:22528
	ds_read_b128 v[218:221], v168 offset:23552
	global_load_lds_dwordx4 v[162:163], off
	s_add_i32 m0, s46, 0x2000
	s_add_u32 s46, s14, 0x4000
	v_lshl_add_u64 v[162:163], s[14:15], 0, v[138:139]
	s_addc_u32 s47, s15, 0
	s_add_i32 s48, s35, s22
	global_load_lds_dwordx4 v[162:163], off
	v_lshl_add_u64 v[162:163], s[46:47], 0, v[142:143]
	s_mov_b32 m0, s48
	s_nop 0
	global_load_lds_dwordx4 v[162:163], off
	v_lshl_add_u64 v[162:163], s[46:47], 0, v[138:139]
	s_add_i32 m0, s48, 0x2000
	s_nop 0
	global_load_lds_dwordx4 v[162:163], off
	s_waitcnt vmcnt(6)
	s_waitcnt lgkmcnt(0)
	s_barrier
; #define PG8_STAGE(bufoff, gbase, voff) do { _Pragma("unroll") for (int _i = 0; _i < 2; ++_i) \
;         __builtin_amdgcn_global_load_lds((const unsigned*)((const char*)(gbase) + (voff)[_i]), (LAS unsigned*)(lds + (bufoff) + ldsw + _i * 8192), 16, 0, 0); } while (0)
; #define PG8_LDA(dst, b, h) do { _Pragma("unroll") for (int m = 0; m < 4; ++m) _Pragma("unroll") for (int k = 0; k < 2; ++k) dst[m][k] = *(const LAS bf16x8*)(lds + PG8_SA(b, h) + aoff + m * 2048 + k * 1024); } while (0)
; #define PG8_LDB(dst, b, h) do { _Pragma("unroll") for (int n = 0; n < 2; ++n) _Pragma("unroll") for (int k = 0; k < 2; ++k) dst[n][k] = *(const LAS bf16x8*)(lds + PG8_SB(b, h) + boff + n * 2048 + k * 1024); } while (0)
; #define PG8_WAIT_V(n) asm volatile("s_waitcnt vmcnt(" #n ")" ::: "memory")
; #define PG8_WAIT_L(n) asm volatile("s_waitcnt lgkmcnt(" #n ")" ::: "memory")
; #define PG8_BAR __builtin_amdgcn_s_barrier()
; #define PG8_SCHED __builtin_amdgcn_sched_barrier(0)
; template <class Epi, class Sched, bool I8 = false>
; __device__ __forceinline__ void gemm_phase(LAS unsigned char* lds, const Gemm g, const Sched& S, const Epi& E) {
;     ...
;             PG8_WAIT_V(8); PG8_WAIT_L(0); PG8_BAR; PG8_MMA(1, 0, At, B0); PG8_MMA(1, 1, At, B1); PG8_BAR; PG8_SCHED;
;             PG8_LDB(B0, 1, 0); PG8_LDB(B1, 1, 1); PG8_SCHED; PG8_LDA(At, 1, 0); PG8_STAGE(PG8_SA(0, 1), a2 + hstepA, voffA);
;             PG8_WAIT_V(8); PG8_WAIT_L(0); PG8_BAR; PG8_MMA(0, 0, At, B0); PG8_MMA(0, 1, At, B1); PG8_BAR; PG8_SCHED;
	s_setprio 1
	s_waitcnt lgkmcnt(0)
	v_mfma_f32_16x16x32_bf16 v[94:97], v[130:133], v[190:193], v[94:97]
	v_mfma_f32_16x16x32_bf16 v[90:93], v[158:161], v[190:193], v[90:93]
	v_mfma_f32_16x16x32_bf16 v[86:89], v[130:133], v[198:201], v[86:89]
	v_mfma_f32_16x16x32_bf16 v[82:85], v[158:161], v[198:201], v[82:85]
	v_mfma_f32_16x16x32_bf16 v[78:81], v[130:133], v[206:209], v[78:81]
	v_mfma_f32_16x16x32_bf16 v[74:77], v[158:161], v[206:209], v[74:77]
	v_mfma_f32_16x16x32_bf16 v[70:73], v[130:133], v[214:217], v[70:73]
	v_mfma_f32_16x16x32_bf16 v[66:69], v[158:161], v[214:217], v[66:69]
	v_mfma_f32_16x16x32_bf16 v[94:97], v[134:137], v[194:197], v[94:97]
	v_mfma_f32_16x16x32_bf16 v[90:93], v[170:173], v[194:197], v[90:93]
	v_mfma_f32_16x16x32_bf16 v[86:89], v[134:137], v[202:205], v[86:89]
	v_mfma_f32_16x16x32_bf16 v[82:85], v[170:173], v[202:205], v[82:85]
	v_mfma_f32_16x16x32_bf16 v[78:81], v[134:137], v[210:213], v[78:81]
	v_mfma_f32_16x16x32_bf16 v[74:77], v[170:173], v[210:213], v[74:77]
	v_mfma_f32_16x16x32_bf16 v[70:73], v[134:137], v[218:221], v[70:73]
	v_mfma_f32_16x16x32_bf16 v[66:69], v[170:173], v[218:221], v[66:69]
	s_setprio 0
	s_setprio 1
	v_mfma_f32_16x16x32_bf16 v[30:33], v[174:177], v[190:193], v[30:33]
	v_mfma_f32_16x16x32_bf16 v[26:29], v[182:185], v[190:193], v[26:29]
	v_mfma_f32_16x16x32_bf16 v[22:25], v[174:177], v[198:201], v[22:25]
	v_mfma_f32_16x16x32_bf16 v[18:21], v[182:185], v[198:201], v[18:21]
	v_mfma_f32_16x16x32_bf16 v[14:17], v[174:177], v[206:209], v[14:17]
	v_mfma_f32_16x16x32_bf16 v[10:13], v[182:185], v[206:209], v[10:13]
	v_mfma_f32_16x16x32_bf16 v[6:9], v[174:177], v[214:217], v[6:9]
	v_mfma_f32_16x16x32_bf16 v[2:5], v[182:185], v[214:217], v[2:5]
	v_mfma_f32_16x16x32_bf16 v[30:33], v[178:181], v[194:197], v[30:33]
	v_mfma_f32_16x16x32_bf16 v[26:29], v[186:189], v[194:197], v[26:29]
	v_mfma_f32_16x16x32_bf16 v[22:25], v[178:181], v[202:205], v[22:25]
	v_mfma_f32_16x16x32_bf16 v[18:21], v[186:189], v[202:205], v[18:21]
	v_mfma_f32_16x16x32_bf16 v[14:17], v[178:181], v[210:213], v[14:17]
	v_mfma_f32_16x16x32_bf16 v[10:13], v[186:189], v[210:213], v[10:13]
	v_mfma_f32_16x16x32_bf16 v[6:9], v[178:181], v[218:221], v[6:9]
	v_mfma_f32_16x16x32_bf16 v[2:5], v[186:189], v[218:221], v[2:5]
	s_setprio 0
	s_barrier
	s_add_i32 s46, 0, 0x18000
	v_add_u32_e32 v155, s46, v165
	s_add_i32 s47, 0, 0x1c000
	ds_read_b128 v[130:133], v155
	ds_read_b128 v[134:137], v155 offset:1024
	ds_read_b128 v[158:161], v155 offset:2048
	ds_read_b128 v[170:173], v155 offset:3072
	v_add_u32_e32 v155, s47, v165
	ds_read_b128 v[174:177], v155
	ds_read_b128 v[178:181], v155 offset:1024
	ds_read_b128 v[182:185], v155 offset:2048
	ds_read_b128 v[186:189], v155 offset:3072
	v_lshl_add_u64 v[162:163], s[16:17], 0, v[144:145]
	s_mov_b32 m0, s26
	s_nop 0
	global_load_lds_dwordx4 v[162:163], off
	v_lshl_add_u64 v[162:163], s[16:17], 0, v[140:141]
	s_mov_b32 m0, s27
	s_nop 0
	global_load_lds_dwordx4 v[162:163], off
	s_add_u32 s16, s16, 0x4000
	s_addc_u32 s17, s17, 0
	s_mov_b32 m0, s28
	v_lshl_add_u64 v[162:163], s[16:17], 0, v[144:145]
	ds_read_b128 v[190:193], v168 offset:32768
	ds_read_b128 v[194:197], v168 offset:33792
	ds_read_b128 v[198:201], v168 offset:34816
	ds_read_b128 v[202:205], v168 offset:35840
	ds_read_b128 v[206:209], v168 offset:36864
	ds_read_b128 v[210:213], v168 offset:37888
	ds_read_b128 v[214:217], v168 offset:38912
	ds_read_b128 v[218:221], v168 offset:39936
	global_load_lds_dwordx4 v[162:163], off
	v_lshl_add_u64 v[162:163], s[16:17], 0, v[140:141]
	s_mov_b32 m0, s29
	s_nop 0
	global_load_lds_dwordx4 v[162:163], off
	s_waitcnt vmcnt(8)
	s_waitcnt lgkmcnt(0)
	s_barrier
; #define PG8_STAGE(bufoff, gbase, voff) do { _Pragma("unroll") for (int _i = 0; _i < 2; ++_i) \
;         __builtin_amdgcn_global_load_lds((const unsigned*)((const char*)(gbase) + (voff)[_i]), (LAS unsigned*)(lds + (bufoff) + ldsw + _i * 8192), 16, 0, 0); } while (0)
; #define PG8_LDA(dst, b, h) do { _Pragma("unroll") for (int m = 0; m < 4; ++m) _Pragma("unroll") for (int k = 0; k < 2; ++k) dst[m][k] = *(const LAS bf16x8*)(lds + PG8_SA(b, h) + aoff + m * 2048 + k * 1024); } while (0)
; #define PG8_WAIT_V(n) asm volatile("s_waitcnt vmcnt(" #n ")" ::: "memory")
; #define PG8_WAIT_L(n) asm volatile("s_waitcnt lgkmcnt(" #n ")" ::: "memory")
; #define PG8_BAR __builtin_amdgcn_s_barrier()
; #define PG8_SCHED __builtin_amdgcn_sched_barrier(0)
; template <class Epi, class Sched, bool I8 = false>
; __device__ __forceinline__ void gemm_phase(LAS unsigned char* lds, const Gemm g, const Sched& S, const Epi& E) {
;     ...
;             PG8_WAIT_V(8); PG8_WAIT_L(0); PG8_BAR; PG8_MMA(0, 0, At, B0); PG8_MMA(0, 1, At, B1); PG8_BAR; PG8_SCHED;
;             PG8_LDA(At, 1, 1); PG8_STAGE(PG8_SB(1, 0), b3, voffB); PG8_STAGE(PG8_SB(1, 1), b3 + hstepB, voffB); PG8_STAGE(PG8_SA(1, 0), a3, voffA);
;             PG8_WAIT_V(8); PG8_WAIT_L(0); PG8_BAR; PG8_MMA(1, 0, At, B0); PG8_MMA(1, 1, At, B1); PG8_BAR; PG8_SCHED;
;         }
;         if (wr == 0) PG8_BAR;
	s_setprio 1
	s_waitcnt lgkmcnt(0)
	v_mfma_f32_16x16x32_bf16 v[126:129], v[130:133], v[190:193], v[126:129]
	v_mfma_f32_16x16x32_bf16 v[122:125], v[158:161], v[190:193], v[122:125]
	v_mfma_f32_16x16x32_bf16 v[118:121], v[130:133], v[198:201], v[118:121]
	v_mfma_f32_16x16x32_bf16 v[114:117], v[158:161], v[198:201], v[114:117]
	v_mfma_f32_16x16x32_bf16 v[110:113], v[130:133], v[206:209], v[110:113]
	v_mfma_f32_16x16x32_bf16 v[106:109], v[158:161], v[206:209], v[106:109]
	v_mfma_f32_16x16x32_bf16 v[102:105], v[130:133], v[214:217], v[102:105]
	v_mfma_f32_16x16x32_bf16 v[98:101], v[158:161], v[214:217], v[98:101]
	v_mfma_f32_16x16x32_bf16 v[126:129], v[134:137], v[194:197], v[126:129]
	v_mfma_f32_16x16x32_bf16 v[122:125], v[170:173], v[194:197], v[122:125]
	v_mfma_f32_16x16x32_bf16 v[118:121], v[134:137], v[202:205], v[118:121]
	v_mfma_f32_16x16x32_bf16 v[114:117], v[170:173], v[202:205], v[114:117]
	v_mfma_f32_16x16x32_bf16 v[110:113], v[134:137], v[210:213], v[110:113]
	v_mfma_f32_16x16x32_bf16 v[106:109], v[170:173], v[210:213], v[106:109]
	v_mfma_f32_16x16x32_bf16 v[102:105], v[134:137], v[218:221], v[102:105]
	v_mfma_f32_16x16x32_bf16 v[98:101], v[170:173], v[218:221], v[98:101]
	s_setprio 0
	s_setprio 1
	v_mfma_f32_16x16x32_bf16 v[62:65], v[174:177], v[190:193], v[62:65]
	v_mfma_f32_16x16x32_bf16 v[58:61], v[182:185], v[190:193], v[58:61]
	v_mfma_f32_16x16x32_bf16 v[54:57], v[174:177], v[198:201], v[54:57]
	v_mfma_f32_16x16x32_bf16 v[50:53], v[182:185], v[198:201], v[50:53]
	v_mfma_f32_16x16x32_bf16 v[46:49], v[174:177], v[206:209], v[46:49]
	v_mfma_f32_16x16x32_bf16 v[42:45], v[182:185], v[206:209], v[42:45]
	v_mfma_f32_16x16x32_bf16 v[38:41], v[174:177], v[214:217], v[38:41]
	v_mfma_f32_16x16x32_bf16 v[34:37], v[182:185], v[214:217], v[34:37]
	v_mfma_f32_16x16x32_bf16 v[62:65], v[178:181], v[194:197], v[62:65]
	v_mfma_f32_16x16x32_bf16 v[58:61], v[186:189], v[194:197], v[58:61]
	v_mfma_f32_16x16x32_bf16 v[54:57], v[178:181], v[202:205], v[54:57]
	v_mfma_f32_16x16x32_bf16 v[50:53], v[186:189], v[202:205], v[50:53]
	v_mfma_f32_16x16x32_bf16 v[46:49], v[178:181], v[210:213], v[46:49]
	v_mfma_f32_16x16x32_bf16 v[42:45], v[186:189], v[210:213], v[42:45]
	v_mfma_f32_16x16x32_bf16 v[38:41], v[178:181], v[218:221], v[38:41]
	v_mfma_f32_16x16x32_bf16 v[34:37], v[186:189], v[218:221], v[34:37]
	s_setprio 0
	s_barrier
	s_add_u32 s16, s14, 0x8000
	s_addc_u32 s17, s15, 0
	s_add_i32 s46, s46, s22
	v_lshl_add_u64 v[162:163], s[16:17], 0, v[142:143]
	s_mov_b32 m0, s46
	ds_read_b128 v[190:193], v168 offset:49152
	ds_read_b128 v[194:197], v168 offset:50176
	ds_read_b128 v[198:201], v168 offset:51200
	ds_read_b128 v[202:205], v168 offset:52224
	ds_read_b128 v[206:209], v168 offset:53248
	ds_read_b128 v[210:213], v168 offset:54272
	ds_read_b128 v[214:217], v168 offset:55296
	ds_read_b128 v[218:221], v168 offset:56320
	global_load_lds_dwordx4 v[162:163], off
	s_add_i32 m0, s46, 0x2000
	s_add_u32 s14, s14, 0xc000
	v_lshl_add_u64 v[162:163], s[16:17], 0, v[138:139]
	s_addc_u32 s15, s15, 0
	s_add_i32 s16, s47, s22
	global_load_lds_dwordx4 v[162:163], off
	v_lshl_add_u64 v[162:163], s[14:15], 0, v[142:143]
	s_mov_b32 m0, s16
	s_nop 0
	global_load_lds_dwordx4 v[162:163], off
	v_lshl_add_u64 v[162:163], s[14:15], 0, v[138:139]
	s_add_i32 m0, s16, 0x2000
	s_nop 0
	global_load_lds_dwordx4 v[162:163], off
	s_waitcnt vmcnt(6)
	s_waitcnt lgkmcnt(0)
	s_barrier
	s_setprio 1
	s_waitcnt lgkmcnt(0)
	v_mfma_f32_16x16x32_bf16 v[94:97], v[130:133], v[190:193], v[94:97]
	v_mfma_f32_16x16x32_bf16 v[90:93], v[158:161], v[190:193], v[90:93]
	v_mfma_f32_16x16x32_bf16 v[86:89], v[130:133], v[198:201], v[86:89]
	v_mfma_f32_16x16x32_bf16 v[82:85], v[158:161], v[198:201], v[82:85]
	v_mfma_f32_16x16x32_bf16 v[78:81], v[130:133], v[206:209], v[78:81]
	v_mfma_f32_16x16x32_bf16 v[74:77], v[158:161], v[206:209], v[74:77]
	v_mfma_f32_16x16x32_bf16 v[70:73], v[130:133], v[214:217], v[70:73]
	v_mfma_f32_16x16x32_bf16 v[66:69], v[158:161], v[214:217], v[66:69]
	v_mfma_f32_16x16x32_bf16 v[94:97], v[134:137], v[194:197], v[94:97]
	v_mfma_f32_16x16x32_bf16 v[90:93], v[170:173], v[194:197], v[90:93]
	v_mfma_f32_16x16x32_bf16 v[86:89], v[134:137], v[202:205], v[86:89]
	v_mfma_f32_16x16x32_bf16 v[82:85], v[170:173], v[202:205], v[82:85]
	v_mfma_f32_16x16x32_bf16 v[78:81], v[134:137], v[210:213], v[78:81]
	v_mfma_f32_16x16x32_bf16 v[74:77], v[170:173], v[210:213], v[74:77]
	v_mfma_f32_16x16x32_bf16 v[70:73], v[134:137], v[218:221], v[70:73]
	v_mfma_f32_16x16x32_bf16 v[66:69], v[170:173], v[218:221], v[66:69]
	s_setprio 0
	s_setprio 1
	v_mfma_f32_16x16x32_bf16 v[30:33], v[174:177], v[190:193], v[30:33]
	v_mfma_f32_16x16x32_bf16 v[26:29], v[182:185], v[190:193], v[26:29]
	v_mfma_f32_16x16x32_bf16 v[22:25], v[174:177], v[198:201], v[22:25]
	v_mfma_f32_16x16x32_bf16 v[18:21], v[182:185], v[198:201], v[18:21]
	v_mfma_f32_16x16x32_bf16 v[14:17], v[174:177], v[206:209], v[14:17]
	v_mfma_f32_16x16x32_bf16 v[10:13], v[182:185], v[206:209], v[10:13]
	v_mfma_f32_16x16x32_bf16 v[6:9], v[174:177], v[214:217], v[6:9]
	v_mfma_f32_16x16x32_bf16 v[2:5], v[182:185], v[214:217], v[2:5]
	v_mfma_f32_16x16x32_bf16 v[30:33], v[178:181], v[194:197], v[30:33]
	v_mfma_f32_16x16x32_bf16 v[26:29], v[186:189], v[194:197], v[26:29]
	v_mfma_f32_16x16x32_bf16 v[22:25], v[178:181], v[202:205], v[22:25]
	v_mfma_f32_16x16x32_bf16 v[18:21], v[186:189], v[202:205], v[18:21]
	v_mfma_f32_16x16x32_bf16 v[14:17], v[178:181], v[210:213], v[14:17]
	v_mfma_f32_16x16x32_bf16 v[10:13], v[186:189], v[210:213], v[10:13]
	v_mfma_f32_16x16x32_bf16 v[6:9], v[178:181], v[218:221], v[6:9]
	v_mfma_f32_16x16x32_bf16 v[2:5], v[186:189], v[218:221], v[2:5]
	s_setprio 0
	s_barrier
	s_add_i32 s45, s45, 2
	s_add_u32 s10, s10, 0x10000
	s_addc_u32 s11, s11, 0
	s_add_u32 s43, s43, 0x10000
	s_addc_u32 s44, s44, 0
	s_cmp_gt_u32 s45, 5
	s_cbranch_scc0 .LBB0_2685
	s_and_b64 vcc, exec, s[6:7]
	s_cbranch_vccz .LBB0_2688
	s_barrier

; #define PG8_STAGE(bufoff, gbase, voff) do { _Pragma("unroll") for (int _i = 0; _i < 2; ++_i) \
;         __builtin_amdgcn_global_load_lds((const unsigned*)((const char*)(gbase) + (voff)[_i]), (LAS unsigned*)(lds + (bufoff) + ldsw + _i * 8192), 16, 0, 0); } while (0)
; #define PG8_LDA(dst, b, h) do { _Pragma("unroll") for (int m = 0; m < 4; ++m) _Pragma("unroll") for (int k = 0; k < 2; ++k) dst[m][k] = *(const LAS bf16x8*)(lds + PG8_SA(b, h) + aoff + m * 2048 + k * 1024); } while (0)
; #define PG8_LDB(dst, b, h) do { _Pragma("unroll") for (int n = 0; n < 2; ++n) _Pragma("unroll") for (int k = 0; k < 2; ++k) dst[n][k] = *(const LAS bf16x8*)(lds + PG8_SB(b, h) + boff + n * 2048 + k * 1024); } while (0)
; #define PG8_WAIT_V(n) asm volatile("s_waitcnt vmcnt(" #n ")" ::: "memory")
; #define PG8_WAIT_L(n) asm volatile("s_waitcnt lgkmcnt(" #n ")" ::: "memory")
; #define PG8_BAR __builtin_amdgcn_s_barrier()
; #define PG8_SCHED __builtin_amdgcn_sched_barrier(0)
; template <class Epi, class Sched, bool I8 = false>
; __device__ __forceinline__ void gemm_phase(LAS unsigned char* lds, const Gemm g, const Sched& S, const Epi& E) {
;     ...
;             const char* a1 = cA + (size_t)(t + 1) * kstep;
;             const char* a2 = last ? nA : cA + (size_t)(t + 2) * kstep; const char* b2 = last ? nB : cB + (size_t)(t + 2) * kstep;
;             const char* a3 = a2 + kstep; const char* b3 = b2 + kstep;
;             PG8_LDB(B0, 0, 0); PG8_LDB(B1, 0, 1); PG8_SCHED; PG8_LDA(At, 0, 0); PG8_STAGE(PG8_SA(1, 1), a1 + hstepA, voffA);
;             PG8_WAIT_V(8); PG8_WAIT_L(0); PG8_BAR; PG8_MMA(0, 0, At, B0); PG8_MMA(0, 1, At, B1); PG8_BAR; PG8_SCHED;
;             PG8_LDA(At, 0, 1); PG8_STAGE(PG8_SB(0, 0), b2, voffB); PG8_STAGE(PG8_SB(0, 1), b2 + hstepB, voffB); PG8_STAGE(PG8_SA(0, 0), a2, voffA);
;             PG8_WAIT_V(8); PG8_WAIT_L(0); PG8_BAR; PG8_MMA(1, 0, At, B0); PG8_MMA(1, 1, At, B1); PG8_BAR; PG8_SCHED;
.LBB0_3744:
	ds_read_b128 v[130:133], v231
	ds_read_b128 v[134:137], v231 offset:1024
	ds_read_b128 v[138:141], v231 offset:2048
	ds_read_b128 v[142:145], v231 offset:3072
	ds_read_b128 v[146:149], v232
	ds_read_b128 v[150:153], v232 offset:1024
	ds_read_b128 v[154:157], v232 offset:2048
	ds_read_b128 v[158:161], v232 offset:3072
	s_add_u32 s34, s30, 0x4000
	s_addc_u32 s35, s31, 0
	s_cmp_eq_u32 s59, 60
	s_cselect_b32 s38, s23, s34
	s_cselect_b32 s39, s5, s35
	s_cselect_b32 s36, s29, s57
	s_cselect_b32 s37, s21, s58
	s_add_u32 s34, s38, 0x8000
	s_addc_u32 s35, s39, 0
	s_sub_u32 s98, s30, 0x4000
	s_subb_u32 s99, s31, 0
	v_lshl_add_u64 v[212:213], s[98:99], 0, v[194:195]
	s_mov_b32 m0, s51
	s_nop 0
	global_load_lds_dwordx4 v[212:213], off
	v_lshl_add_u64 v[212:213], s[98:99], 0, v[198:199]
	s_mov_b32 m0, s52
	s_nop 0
	global_load_lds_dwordx4 v[212:213], off
	v_lshl_add_u64 v[212:213], s[30:31], 0, v[204:205]
	s_add_i32 m0, s44, 0xc000
	ds_read_b128 v[162:165], v233
	ds_read_b128 v[166:169], v233 offset:1024
	ds_read_b128 v[170:173], v233 offset:2048
	ds_read_b128 v[174:177], v233 offset:3072
	ds_read_b128 v[178:181], v233 offset:4096
	ds_read_b128 v[182:185], v233 offset:5120
	ds_read_b128 v[186:189], v233 offset:6144
	ds_read_b128 v[190:193], v233 offset:7168
	global_load_lds_dwordx4 v[212:213], off
	v_lshl_add_u64 v[212:213], s[30:31], 0, v[206:207]
	s_add_i32 m0, s44, 0xe000
	s_nop 0
	global_load_lds_dwordx4 v[212:213], off
	s_waitcnt vmcnt(8)
	s_waitcnt lgkmcnt(0)
	s_barrier
	s_setprio 1
	s_waitcnt lgkmcnt(0)
	v_mfma_f32_16x16x32_bf16 v[126:129], v[130:133], v[162:165], v[126:129]
	v_mfma_f32_16x16x32_bf16 v[122:125], v[138:141], v[162:165], v[122:125]
	v_mfma_f32_16x16x32_bf16 v[118:121], v[130:133], v[170:173], v[118:121]
	v_mfma_f32_16x16x32_bf16 v[110:113], v[138:141], v[170:173], v[110:113]
	v_mfma_f32_16x16x32_bf16 v[102:105], v[130:133], v[178:181], v[102:105]
	v_mfma_f32_16x16x32_bf16 v[94:97], v[138:141], v[178:181], v[94:97]
	v_mfma_f32_16x16x32_bf16 v[86:89], v[130:133], v[186:189], v[86:89]
	v_mfma_f32_16x16x32_bf16 v[78:81], v[138:141], v[186:189], v[78:81]
	v_mfma_f32_16x16x32_bf16 v[126:129], v[134:137], v[166:169], v[126:129]
	v_mfma_f32_16x16x32_bf16 v[122:125], v[142:145], v[166:169], v[122:125]
	v_mfma_f32_16x16x32_bf16 v[118:121], v[134:137], v[174:177], v[118:121]
	v_mfma_f32_16x16x32_bf16 v[110:113], v[142:145], v[174:177], v[110:113]
	v_mfma_f32_16x16x32_bf16 v[102:105], v[134:137], v[182:185], v[102:105]
	v_mfma_f32_16x16x32_bf16 v[94:97], v[142:145], v[182:185], v[94:97]
	v_mfma_f32_16x16x32_bf16 v[86:89], v[134:137], v[190:193], v[86:89]
	v_mfma_f32_16x16x32_bf16 v[78:81], v[142:145], v[190:193], v[78:81]
	s_setprio 0
	s_setprio 1
	v_mfma_f32_16x16x32_bf16 v[114:117], v[146:149], v[162:165], v[114:117]
	v_mfma_f32_16x16x32_bf16 v[106:109], v[154:157], v[162:165], v[106:109]
	v_mfma_f32_16x16x32_bf16 v[98:101], v[146:149], v[170:173], v[98:101]
	v_mfma_f32_16x16x32_bf16 v[90:93], v[154:157], v[170:173], v[90:93]
	v_mfma_f32_16x16x32_bf16 v[82:85], v[146:149], v[178:181], v[82:85]
	v_mfma_f32_16x16x32_bf16 v[74:77], v[154:157], v[178:181], v[74:77]
	v_mfma_f32_16x16x32_bf16 v[70:73], v[146:149], v[186:189], v[70:73]
	v_mfma_f32_16x16x32_bf16 v[66:69], v[154:157], v[186:189], v[66:69]
	v_mfma_f32_16x16x32_bf16 v[114:117], v[150:153], v[166:169], v[114:117]
	v_mfma_f32_16x16x32_bf16 v[106:109], v[158:161], v[166:169], v[106:109]
	v_mfma_f32_16x16x32_bf16 v[98:101], v[150:153], v[174:177], v[98:101]
	v_mfma_f32_16x16x32_bf16 v[90:93], v[158:161], v[174:177], v[90:93]
	v_mfma_f32_16x16x32_bf16 v[82:85], v[150:153], v[182:185], v[82:85]
	v_mfma_f32_16x16x32_bf16 v[74:77], v[158:161], v[182:185], v[74:77]
	v_mfma_f32_16x16x32_bf16 v[70:73], v[150:153], v[190:193], v[70:73]
	v_mfma_f32_16x16x32_bf16 v[66:69], v[158:161], v[190:193], v[66:69]
	s_setprio 0
	s_barrier
	s_add_i32 s60, s55, s43
	v_lshl_add_u64 v[212:213], s[36:37], 0, v[196:197]
	s_mov_b32 m0, s60
	ds_read_b128 v[162:165], v233 offset:16384
	ds_read_b128 v[166:169], v233 offset:17408
	ds_read_b128 v[170:173], v233 offset:18432
	ds_read_b128 v[174:177], v233 offset:19456
	ds_read_b128 v[178:181], v233 offset:20480
	ds_read_b128 v[182:185], v233 offset:21504
	ds_read_b128 v[186:189], v233 offset:22528
	ds_read_b128 v[190:193], v233 offset:23552
	global_load_lds_dwordx4 v[212:213], off
	s_add_i32 m0, s60, 0x2000
	s_add_u32 s60, s36, 0x4000
	v_lshl_add_u64 v[212:213], s[36:37], 0, v[200:201]
	s_addc_u32 s61, s37, 0
	s_add_i32 s62, s56, s43
	global_load_lds_dwordx4 v[212:213], off
	v_lshl_add_u64 v[212:213], s[60:61], 0, v[196:197]
	s_mov_b32 m0, s62
	s_nop 0
	global_load_lds_dwordx4 v[212:213], off
	v_lshl_add_u64 v[212:213], s[60:61], 0, v[200:201]
	s_add_i32 m0, s62, 0x2000
	s_nop 0
	global_load_lds_dwordx4 v[212:213], off
	s_waitcnt vmcnt(6)
	s_waitcnt lgkmcnt(0)
	s_barrier
; #define PG8_STAGE(bufoff, gbase, voff) do { _Pragma("unroll") for (int _i = 0; _i < 2; ++_i) \
;         __builtin_amdgcn_global_load_lds((const unsigned*)((const char*)(gbase) + (voff)[_i]), (LAS unsigned*)(lds + (bufoff) + ldsw + _i * 8192), 16, 0, 0); } while (0)
; #define PG8_LDA(dst, b, h) do { _Pragma("unroll") for (int m = 0; m < 4; ++m) _Pragma("unroll") for (int k = 0; k < 2; ++k) dst[m][k] = *(const LAS bf16x8*)(lds + PG8_SA(b, h) + aoff + m * 2048 + k * 1024); } while (0)
; #define PG8_LDB(dst, b, h) do { _Pragma("unroll") for (int n = 0; n < 2; ++n) _Pragma("unroll") for (int k = 0; k < 2; ++k) dst[n][k] = *(const LAS bf16x8*)(lds + PG8_SB(b, h) + boff + n * 2048 + k * 1024); } while (0)
; #define PG8_WAIT_V(n) asm volatile("s_waitcnt vmcnt(" #n ")" ::: "memory")
; #define PG8_WAIT_L(n) asm volatile("s_waitcnt lgkmcnt(" #n ")" ::: "memory")
; #define PG8_BAR __builtin_amdgcn_s_barrier()
; #define PG8_SCHED __builtin_amdgcn_sched_barrier(0)
; template <class Epi, class Sched, bool I8 = false>
; __device__ __forceinline__ void gemm_phase(LAS unsigned char* lds, const Gemm g, const Sched& S, const Epi& E) {
;     ...
;             PG8_WAIT_V(8); PG8_WAIT_L(0); PG8_BAR; PG8_MMA(1, 0, At, B0); PG8_MMA(1, 1, At, B1); PG8_BAR; PG8_SCHED;
;             PG8_LDB(B0, 1, 0); PG8_LDB(B1, 1, 1); PG8_SCHED; PG8_LDA(At, 1, 0); PG8_STAGE(PG8_SA(0, 1), a2 + hstepA, voffA);
;             PG8_WAIT_V(8); PG8_WAIT_L(0); PG8_BAR; PG8_MMA(0, 0, At, B0); PG8_MMA(0, 1, At, B1); PG8_BAR; PG8_SCHED;
	s_setprio 1
	s_waitcnt lgkmcnt(0)
	v_mfma_f32_16x16x32_bf16 v[62:65], v[130:133], v[162:165], v[62:65]
	v_mfma_f32_16x16x32_bf16 v[58:61], v[138:141], v[162:165], v[58:61]
	v_mfma_f32_16x16x32_bf16 v[54:57], v[130:133], v[170:173], v[54:57]
	v_mfma_f32_16x16x32_bf16 v[46:49], v[138:141], v[170:173], v[46:49]
	v_mfma_f32_16x16x32_bf16 v[38:41], v[130:133], v[178:181], v[38:41]
	v_mfma_f32_16x16x32_bf16 v[30:33], v[138:141], v[178:181], v[30:33]
	v_mfma_f32_16x16x32_bf16 v[22:25], v[130:133], v[186:189], v[22:25]
	v_mfma_f32_16x16x32_bf16 v[14:17], v[138:141], v[186:189], v[14:17]
	v_mfma_f32_16x16x32_bf16 v[62:65], v[134:137], v[166:169], v[62:65]
	v_mfma_f32_16x16x32_bf16 v[58:61], v[142:145], v[166:169], v[58:61]
	v_mfma_f32_16x16x32_bf16 v[54:57], v[134:137], v[174:177], v[54:57]
	v_mfma_f32_16x16x32_bf16 v[46:49], v[142:145], v[174:177], v[46:49]
	v_mfma_f32_16x16x32_bf16 v[38:41], v[134:137], v[182:185], v[38:41]
	v_mfma_f32_16x16x32_bf16 v[30:33], v[142:145], v[182:185], v[30:33]
	v_mfma_f32_16x16x32_bf16 v[22:25], v[134:137], v[190:193], v[22:25]
	v_mfma_f32_16x16x32_bf16 v[14:17], v[142:145], v[190:193], v[14:17]
	s_setprio 0
	s_setprio 1
	v_mfma_f32_16x16x32_bf16 v[50:53], v[146:149], v[162:165], v[50:53]
	v_mfma_f32_16x16x32_bf16 v[42:45], v[154:157], v[162:165], v[42:45]
	v_mfma_f32_16x16x32_bf16 v[34:37], v[146:149], v[170:173], v[34:37]
	v_mfma_f32_16x16x32_bf16 v[26:29], v[154:157], v[170:173], v[26:29]
	v_mfma_f32_16x16x32_bf16 v[18:21], v[146:149], v[178:181], v[18:21]
	v_mfma_f32_16x16x32_bf16 v[10:13], v[154:157], v[178:181], v[10:13]
	v_mfma_f32_16x16x32_bf16 v[6:9], v[146:149], v[186:189], v[6:9]
	v_mfma_f32_16x16x32_bf16 v[2:5], v[154:157], v[186:189], v[2:5]
	v_mfma_f32_16x16x32_bf16 v[50:53], v[150:153], v[166:169], v[50:53]
	v_mfma_f32_16x16x32_bf16 v[42:45], v[158:161], v[166:169], v[42:45]
	v_mfma_f32_16x16x32_bf16 v[34:37], v[150:153], v[174:177], v[34:37]
	v_mfma_f32_16x16x32_bf16 v[26:29], v[158:161], v[174:177], v[26:29]
	v_mfma_f32_16x16x32_bf16 v[18:21], v[150:153], v[182:185], v[18:21]
	v_mfma_f32_16x16x32_bf16 v[10:13], v[158:161], v[182:185], v[10:13]
	v_mfma_f32_16x16x32_bf16 v[6:9], v[150:153], v[190:193], v[6:9]
	v_mfma_f32_16x16x32_bf16 v[2:5], v[158:161], v[190:193], v[2:5]
	s_setprio 0
	s_barrier
	s_add_i32 s60, 0, 0x18000
	s_add_i32 s61, 0, 0x1c000
	v_add_u32_e32 v142, s60, v230
	v_add_u32_e32 v158, s61, v230
	ds_read_b128 v[130:133], v142
	ds_read_b128 v[134:137], v142 offset:1024
	ds_read_b128 v[138:141], v142 offset:2048
	ds_read_b128 v[142:145], v142 offset:3072
	ds_read_b128 v[146:149], v158
	ds_read_b128 v[150:153], v158 offset:1024
	ds_read_b128 v[154:157], v158 offset:2048
	ds_read_b128 v[158:161], v158 offset:3072
	v_lshl_add_u64 v[212:213], s[38:39], 0, v[194:195]
	s_mov_b32 m0, s44
	s_nop 0
	global_load_lds_dwordx4 v[212:213], off
	v_lshl_add_u64 v[212:213], s[38:39], 0, v[198:199]
	s_mov_b32 m0, s45
	s_nop 0
	global_load_lds_dwordx4 v[212:213], off
	s_add_u32 s38, s38, 0x4000
	s_addc_u32 s39, s39, 0
	s_mov_b32 m0, s46
	v_lshl_add_u64 v[212:213], s[38:39], 0, v[194:195]
	ds_read_b128 v[162:165], v233 offset:32768
	ds_read_b128 v[166:169], v233 offset:33792
	ds_read_b128 v[170:173], v233 offset:34816
	ds_read_b128 v[174:177], v233 offset:35840
	ds_read_b128 v[178:181], v233 offset:36864
	ds_read_b128 v[182:185], v233 offset:37888
	ds_read_b128 v[186:189], v233 offset:38912
	ds_read_b128 v[190:193], v233 offset:39936
	global_load_lds_dwordx4 v[212:213], off
	v_lshl_add_u64 v[212:213], s[38:39], 0, v[198:199]
	s_mov_b32 m0, s47
	s_nop 0
	global_load_lds_dwordx4 v[212:213], off
	s_waitcnt vmcnt(8)
	s_waitcnt lgkmcnt(0)
	s_barrier
; #define PG8_STAGE(bufoff, gbase, voff) do { _Pragma("unroll") for (int _i = 0; _i < 2; ++_i) \
;         __builtin_amdgcn_global_load_lds((const unsigned*)((const char*)(gbase) + (voff)[_i]), (LAS unsigned*)(lds + (bufoff) + ldsw + _i * 8192), 16, 0, 0); } while (0)
; #define PG8_LDA(dst, b, h) do { _Pragma("unroll") for (int m = 0; m < 4; ++m) _Pragma("unroll") for (int k = 0; k < 2; ++k) dst[m][k] = *(const LAS bf16x8*)(lds + PG8_SA(b, h) + aoff + m * 2048 + k * 1024); } while (0)
; #define PG8_WAIT_V(n) asm volatile("s_waitcnt vmcnt(" #n ")" ::: "memory")
; #define PG8_WAIT_L(n) asm volatile("s_waitcnt lgkmcnt(" #n ")" ::: "memory")
; #define PG8_BAR __builtin_amdgcn_s_barrier()
; #define PG8_SCHED __builtin_amdgcn_sched_barrier(0)
; template <class Epi, class Sched, bool I8 = false>
; __device__ __forceinline__ void gemm_phase(LAS unsigned char* lds, const Gemm g, const Sched& S, const Epi& E) {
;     ...
;             PG8_WAIT_V(8); PG8_WAIT_L(0); PG8_BAR; PG8_MMA(0, 0, At, B0); PG8_MMA(0, 1, At, B1); PG8_BAR; PG8_SCHED;
;             PG8_LDA(At, 1, 1); PG8_STAGE(PG8_SB(1, 0), b3, voffB); PG8_STAGE(PG8_SB(1, 1), b3 + hstepB, voffB); PG8_STAGE(PG8_SA(1, 0), a3, voffA);
;             PG8_WAIT_V(8); PG8_WAIT_L(0); PG8_BAR; PG8_MMA(1, 0, At, B0); PG8_MMA(1, 1, At, B1); PG8_BAR; PG8_SCHED;
;         }
;         if (wr == 0) PG8_BAR;
	s_setprio 1
	s_waitcnt lgkmcnt(0)
	v_mfma_f32_16x16x32_bf16 v[126:129], v[130:133], v[162:165], v[126:129]
	v_mfma_f32_16x16x32_bf16 v[122:125], v[138:141], v[162:165], v[122:125]
	v_mfma_f32_16x16x32_bf16 v[118:121], v[130:133], v[170:173], v[118:121]
	v_mfma_f32_16x16x32_bf16 v[110:113], v[138:141], v[170:173], v[110:113]
	v_mfma_f32_16x16x32_bf16 v[102:105], v[130:133], v[178:181], v[102:105]
	v_mfma_f32_16x16x32_bf16 v[94:97], v[138:141], v[178:181], v[94:97]
	v_mfma_f32_16x16x32_bf16 v[86:89], v[130:133], v[186:189], v[86:89]
	v_mfma_f32_16x16x32_bf16 v[78:81], v[138:141], v[186:189], v[78:81]
	v_mfma_f32_16x16x32_bf16 v[126:129], v[134:137], v[166:169], v[126:129]
	v_mfma_f32_16x16x32_bf16 v[122:125], v[142:145], v[166:169], v[122:125]
	v_mfma_f32_16x16x32_bf16 v[118:121], v[134:137], v[174:177], v[118:121]
	v_mfma_f32_16x16x32_bf16 v[110:113], v[142:145], v[174:177], v[110:113]
	v_mfma_f32_16x16x32_bf16 v[102:105], v[134:137], v[182:185], v[102:105]
	v_mfma_f32_16x16x32_bf16 v[94:97], v[142:145], v[182:185], v[94:97]
	v_mfma_f32_16x16x32_bf16 v[86:89], v[134:137], v[190:193], v[86:89]
	v_mfma_f32_16x16x32_bf16 v[78:81], v[142:145], v[190:193], v[78:81]
	s_setprio 0
	s_setprio 1
	v_mfma_f32_16x16x32_bf16 v[114:117], v[146:149], v[162:165], v[114:117]
	v_mfma_f32_16x16x32_bf16 v[106:109], v[154:157], v[162:165], v[106:109]
	v_mfma_f32_16x16x32_bf16 v[98:101], v[146:149], v[170:173], v[98:101]
	v_mfma_f32_16x16x32_bf16 v[90:93], v[154:157], v[170:173], v[90:93]
	v_mfma_f32_16x16x32_bf16 v[82:85], v[146:149], v[178:181], v[82:85]
	v_mfma_f32_16x16x32_bf16 v[74:77], v[154:157], v[178:181], v[74:77]
	v_mfma_f32_16x16x32_bf16 v[70:73], v[146:149], v[186:189], v[70:73]
	v_mfma_f32_16x16x32_bf16 v[66:69], v[154:157], v[186:189], v[66:69]
	v_mfma_f32_16x16x32_bf16 v[114:117], v[150:153], v[166:169], v[114:117]
	v_mfma_f32_16x16x32_bf16 v[106:109], v[158:161], v[166:169], v[106:109]
	v_mfma_f32_16x16x32_bf16 v[98:101], v[150:153], v[174:177], v[98:101]
	v_mfma_f32_16x16x32_bf16 v[90:93], v[158:161], v[174:177], v[90:93]
	v_mfma_f32_16x16x32_bf16 v[82:85], v[150:153], v[182:185], v[82:85]
	v_mfma_f32_16x16x32_bf16 v[74:77], v[158:161], v[182:185], v[74:77]
	v_mfma_f32_16x16x32_bf16 v[70:73], v[150:153], v[190:193], v[70:73]
	v_mfma_f32_16x16x32_bf16 v[66:69], v[158:161], v[190:193], v[66:69]
	s_setprio 0
	s_barrier
	s_add_u32 s38, s36, 0x8000
	s_addc_u32 s39, s37, 0
	s_add_i32 s60, s60, s43
	v_lshl_add_u64 v[212:213], s[38:39], 0, v[196:197]
	s_mov_b32 m0, s60
	ds_read_b128 v[162:165], v233 offset:49152
	ds_read_b128 v[166:169], v233 offset:50176
	ds_read_b128 v[170:173], v233 offset:51200
	ds_read_b128 v[174:177], v233 offset:52224
	ds_read_b128 v[178:181], v233 offset:53248
	ds_read_b128 v[182:185], v233 offset:54272
	ds_read_b128 v[186:189], v233 offset:55296
	ds_read_b128 v[190:193], v233 offset:56320
	global_load_lds_dwordx4 v[212:213], off
	s_add_i32 m0, s60, 0x2000
	s_add_u32 s36, s36, 0xc000
	v_lshl_add_u64 v[212:213], s[38:39], 0, v[200:201]
	s_addc_u32 s37, s37, 0
	s_add_i32 s38, s61, s43
	global_load_lds_dwordx4 v[212:213], off
	v_lshl_add_u64 v[212:213], s[36:37], 0, v[196:197]
	s_mov_b32 m0, s38
	s_nop 0
	global_load_lds_dwordx4 v[212:213], off
	v_lshl_add_u64 v[212:213], s[36:37], 0, v[200:201]
	s_add_i32 m0, s38, 0x2000
	s_nop 0
	global_load_lds_dwordx4 v[212:213], off
	s_waitcnt vmcnt(6)
	s_waitcnt lgkmcnt(0)
	s_barrier
	s_setprio 1
	s_waitcnt lgkmcnt(0)
	v_mfma_f32_16x16x32_bf16 v[62:65], v[130:133], v[162:165], v[62:65]
	v_mfma_f32_16x16x32_bf16 v[58:61], v[138:141], v[162:165], v[58:61]
	v_mfma_f32_16x16x32_bf16 v[54:57], v[130:133], v[170:173], v[54:57]
	v_mfma_f32_16x16x32_bf16 v[46:49], v[138:141], v[170:173], v[46:49]
	v_mfma_f32_16x16x32_bf16 v[38:41], v[130:133], v[178:181], v[38:41]
	v_mfma_f32_16x16x32_bf16 v[30:33], v[138:141], v[178:181], v[30:33]
	v_mfma_f32_16x16x32_bf16 v[22:25], v[130:133], v[186:189], v[22:25]
	v_mfma_f32_16x16x32_bf16 v[14:17], v[138:141], v[186:189], v[14:17]
	v_mfma_f32_16x16x32_bf16 v[62:65], v[134:137], v[166:169], v[62:65]
	v_mfma_f32_16x16x32_bf16 v[58:61], v[142:145], v[166:169], v[58:61]
	v_mfma_f32_16x16x32_bf16 v[54:57], v[134:137], v[174:177], v[54:57]
	v_mfma_f32_16x16x32_bf16 v[46:49], v[142:145], v[174:177], v[46:49]
	v_mfma_f32_16x16x32_bf16 v[38:41], v[134:137], v[182:185], v[38:41]
	v_mfma_f32_16x16x32_bf16 v[30:33], v[142:145], v[182:185], v[30:33]
	v_mfma_f32_16x16x32_bf16 v[22:25], v[134:137], v[190:193], v[22:25]
	v_mfma_f32_16x16x32_bf16 v[14:17], v[142:145], v[190:193], v[14:17]
	s_setprio 0
	s_setprio 1
	v_mfma_f32_16x16x32_bf16 v[50:53], v[146:149], v[162:165], v[50:53]
	v_mfma_f32_16x16x32_bf16 v[42:45], v[154:157], v[162:165], v[42:45]
	v_mfma_f32_16x16x32_bf16 v[34:37], v[146:149], v[170:173], v[34:37]
	v_mfma_f32_16x16x32_bf16 v[26:29], v[154:157], v[170:173], v[26:29]
	v_mfma_f32_16x16x32_bf16 v[18:21], v[146:149], v[178:181], v[18:21]
	v_mfma_f32_16x16x32_bf16 v[10:13], v[154:157], v[178:181], v[10:13]
	v_mfma_f32_16x16x32_bf16 v[6:9], v[146:149], v[186:189], v[6:9]
	v_mfma_f32_16x16x32_bf16 v[2:5], v[154:157], v[186:189], v[2:5]
	v_mfma_f32_16x16x32_bf16 v[50:53], v[150:153], v[166:169], v[50:53]
	v_mfma_f32_16x16x32_bf16 v[42:45], v[158:161], v[166:169], v[42:45]
	v_mfma_f32_16x16x32_bf16 v[34:37], v[150:153], v[174:177], v[34:37]
	v_mfma_f32_16x16x32_bf16 v[26:29], v[158:161], v[174:177], v[26:29]
	v_mfma_f32_16x16x32_bf16 v[18:21], v[150:153], v[182:185], v[18:21]
	v_mfma_f32_16x16x32_bf16 v[10:13], v[158:161], v[182:185], v[10:13]
	v_mfma_f32_16x16x32_bf16 v[6:9], v[150:153], v[190:193], v[6:9]
	v_mfma_f32_16x16x32_bf16 v[2:5], v[158:161], v[190:193], v[2:5]
	s_setprio 0
	s_barrier
	s_add_i32 s59, s59, 2
	s_add_u32 s30, s30, 0x10000
	s_addc_u32 s31, s31, 0
	s_add_u32 s57, s57, 0x10000
	s_addc_u32 s58, s58, 0
	s_cmp_gt_u32 s59, 61
	s_cbranch_scc0 .LBB0_3744
	s_and_b64 vcc, exec, s[6:7]
	s_cbranch_vccz .LBB0_3747
	s_barrier

; #define PG8_STAGE(bufoff, gbase, voff) do { _Pragma("unroll") for (int _i = 0; _i < 2; ++_i) \
;         __builtin_amdgcn_global_load_lds((const unsigned*)((const char*)(gbase) + (voff)[_i]), (LAS unsigned*)(lds + (bufoff) + ldsw + _i * 8192), 16, 0, 0); } while (0)
; #define PG8_LDA(dst, b, h) do { _Pragma("unroll") for (int m = 0; m < 4; ++m) _Pragma("unroll") for (int k = 0; k < 2; ++k) dst[m][k] = *(const LAS bf16x8*)(lds + PG8_SA(b, h) + aoff + m * 2048 + k * 1024); } while (0)
; #define PG8_LDB(dst, b, h) do { _Pragma("unroll") for (int n = 0; n < 2; ++n) _Pragma("unroll") for (int k = 0; k < 2; ++k) dst[n][k] = *(const LAS bf16x8*)(lds + PG8_SB(b, h) + boff + n * 2048 + k * 1024); } while (0)
; #define PG8_WAIT_V(n) asm volatile("s_waitcnt vmcnt(" #n ")" ::: "memory")
; #define PG8_WAIT_L(n) asm volatile("s_waitcnt lgkmcnt(" #n ")" ::: "memory")
; #define PG8_BAR __builtin_amdgcn_s_barrier()
; #define PG8_SCHED __builtin_amdgcn_sched_barrier(0)
; template <class Epi, class Sched, bool I8 = false>
; __device__ __forceinline__ void gemm_phase(LAS unsigned char* lds, const Gemm g, const Sched& S, const Epi& E) {
;     ...
;             const char* a1 = cA + (size_t)(t + 1) * kstep;
;             const char* a2 = last ? nA : cA + (size_t)(t + 2) * kstep; const char* b2 = last ? nB : cB + (size_t)(t + 2) * kstep;
;             const char* a3 = a2 + kstep; const char* b3 = b2 + kstep;
;             PG8_LDB(B0, 0, 0); PG8_LDB(B1, 0, 1); PG8_SCHED; PG8_LDA(At, 0, 0); PG8_STAGE(PG8_SA(1, 1), a1 + hstepA, voffA);
;             PG8_WAIT_V(8); PG8_WAIT_L(0); PG8_BAR; PG8_MMA(0, 0, At, B0); PG8_MMA(0, 1, At, B1); PG8_BAR; PG8_SCHED;
;             PG8_LDA(At, 0, 1); PG8_STAGE(PG8_SB(0, 0), b2, voffB); PG8_STAGE(PG8_SB(0, 1), b2 + hstepB, voffB); PG8_STAGE(PG8_SA(0, 0), a2, voffA);
;             PG8_WAIT_V(8); PG8_WAIT_L(0); PG8_BAR; PG8_MMA(1, 0, At, B0); PG8_MMA(1, 1, At, B1); PG8_BAR; PG8_SCHED;
.LBB0_4168:
	ds_read_b128 v[66:69], v178
	ds_read_b128 v[70:73], v178 offset:1024
	ds_read_b128 v[74:77], v178 offset:2048
	ds_read_b128 v[78:81], v178 offset:3072
	ds_read_b128 v[146:149], v179
	ds_read_b128 v[150:153], v179 offset:1024
	ds_read_b128 v[172:175], v179 offset:2048
	ds_read_b128 v[182:185], v179 offset:3072
	s_add_u32 s22, s20, 0x4000
	s_addc_u32 s23, s21, 0
	s_cmpk_eq_i32 s51, 0x52
	s_cselect_b32 s26, s0, s22
	s_cselect_b32 s27, s1, s23
	s_cselect_b32 s24, s18, s49
	s_cselect_b32 s25, s19, s50
	s_add_u32 s22, s26, 0x8000
	s_addc_u32 s23, s27, 0
	s_sub_u32 s98, s20, 0x4000
	s_subb_u32 s99, s21, 0
	v_lshl_add_u64 v[218:219], s[98:99], 0, v[154:155]
	s_mov_b32 m0, s39
	s_nop 0
	global_load_lds_dwordx4 v[218:219], off
	v_lshl_add_u64 v[218:219], s[98:99], 0, v[158:159]
	s_mov_b32 m0, s40
	s_nop 0
	global_load_lds_dwordx4 v[218:219], off
	v_lshl_add_u64 v[218:219], s[20:21], 0, v[164:165]
	s_add_i32 m0, s34, 0xc000
	ds_read_b128 v[186:189], v180
	ds_read_b128 v[190:193], v180 offset:1024
	ds_read_b128 v[194:197], v180 offset:2048
	ds_read_b128 v[198:201], v180 offset:3072
	ds_read_b128 v[202:205], v180 offset:4096
	ds_read_b128 v[206:209], v180 offset:5120
	ds_read_b128 v[210:213], v180 offset:6144
	ds_read_b128 v[214:217], v180 offset:7168
	global_load_lds_dwordx4 v[218:219], off
	v_lshl_add_u64 v[218:219], s[20:21], 0, v[166:167]
	s_add_i32 m0, s34, 0xe000
	s_nop 0
	global_load_lds_dwordx4 v[218:219], off
	s_waitcnt vmcnt(8)
	s_waitcnt lgkmcnt(0)
	s_barrier
	s_setprio 1
	s_waitcnt lgkmcnt(0)
	v_mfma_i32_16x16x64_i8 v[142:145], v[66:69], v[186:189], v[142:145]
	v_mfma_i32_16x16x64_i8 v[138:141], v[74:77], v[186:189], v[138:141]
	v_mfma_i32_16x16x64_i8 v[126:129], v[66:69], v[194:197], v[126:129]
	v_mfma_i32_16x16x64_i8 v[122:125], v[74:77], v[194:197], v[122:125]
	v_mfma_i32_16x16x64_i8 v[110:113], v[66:69], v[202:205], v[110:113]
	v_mfma_i32_16x16x64_i8 v[106:109], v[74:77], v[202:205], v[106:109]
	v_mfma_i32_16x16x64_i8 v[94:97], v[66:69], v[210:213], v[94:97]
	v_mfma_i32_16x16x64_i8 v[90:93], v[74:77], v[210:213], v[90:93]
	v_mfma_i32_16x16x64_i8 v[142:145], v[70:73], v[190:193], v[142:145]
	v_mfma_i32_16x16x64_i8 v[138:141], v[78:81], v[190:193], v[138:141]
	v_mfma_i32_16x16x64_i8 v[126:129], v[70:73], v[198:201], v[126:129]
	v_mfma_i32_16x16x64_i8 v[122:125], v[78:81], v[198:201], v[122:125]
	v_mfma_i32_16x16x64_i8 v[110:113], v[70:73], v[206:209], v[110:113]
	v_mfma_i32_16x16x64_i8 v[106:109], v[78:81], v[206:209], v[106:109]
	v_mfma_i32_16x16x64_i8 v[94:97], v[70:73], v[214:217], v[94:97]
	v_mfma_i32_16x16x64_i8 v[90:93], v[78:81], v[214:217], v[90:93]
	s_setprio 0
	s_setprio 1
	v_mfma_i32_16x16x64_i8 v[134:137], v[146:149], v[186:189], v[134:137]
	v_mfma_i32_16x16x64_i8 v[130:133], v[172:175], v[186:189], v[130:133]
	v_mfma_i32_16x16x64_i8 v[118:121], v[146:149], v[194:197], v[118:121]
	v_mfma_i32_16x16x64_i8 v[114:117], v[172:175], v[194:197], v[114:117]
	v_mfma_i32_16x16x64_i8 v[102:105], v[146:149], v[202:205], v[102:105]
	v_mfma_i32_16x16x64_i8 v[98:101], v[172:175], v[202:205], v[98:101]
	v_mfma_i32_16x16x64_i8 v[86:89], v[146:149], v[210:213], v[86:89]
	v_mfma_i32_16x16x64_i8 v[82:85], v[172:175], v[210:213], v[82:85]
	v_mfma_i32_16x16x64_i8 v[134:137], v[150:153], v[190:193], v[134:137]
	v_mfma_i32_16x16x64_i8 v[130:133], v[182:185], v[190:193], v[130:133]
	v_mfma_i32_16x16x64_i8 v[118:121], v[150:153], v[198:201], v[118:121]
	v_mfma_i32_16x16x64_i8 v[114:117], v[182:185], v[198:201], v[114:117]
	v_mfma_i32_16x16x64_i8 v[102:105], v[150:153], v[206:209], v[102:105]
	v_mfma_i32_16x16x64_i8 v[98:101], v[182:185], v[206:209], v[98:101]
	v_mfma_i32_16x16x64_i8 v[86:89], v[150:153], v[214:217], v[86:89]
	v_mfma_i32_16x16x64_i8 v[82:85], v[182:185], v[214:217], v[82:85]
	s_setprio 0
	s_barrier
	s_add_i32 s52, s43, s33
	v_lshl_add_u64 v[218:219], s[24:25], 0, v[156:157]
	s_mov_b32 m0, s52
	ds_read_b128 v[186:189], v180 offset:16384
	ds_read_b128 v[190:193], v180 offset:17408
	ds_read_b128 v[194:197], v180 offset:18432
	ds_read_b128 v[198:201], v180 offset:19456
	ds_read_b128 v[202:205], v180 offset:20480
	ds_read_b128 v[206:209], v180 offset:21504
	ds_read_b128 v[210:213], v180 offset:22528
	ds_read_b128 v[214:217], v180 offset:23552
	global_load_lds_dwordx4 v[218:219], off
	s_add_i32 m0, s52, 0x2000
	s_add_u32 s52, s24, 0x4000
	v_lshl_add_u64 v[218:219], s[24:25], 0, v[160:161]
	s_addc_u32 s53, s25, 0
	s_add_i32 s54, s44, s33
	global_load_lds_dwordx4 v[218:219], off
	v_lshl_add_u64 v[218:219], s[52:53], 0, v[156:157]
	s_mov_b32 m0, s54
	s_nop 0
	global_load_lds_dwordx4 v[218:219], off
	v_lshl_add_u64 v[218:219], s[52:53], 0, v[160:161]
	s_add_i32 m0, s54, 0x2000
	s_nop 0
	global_load_lds_dwordx4 v[218:219], off
	s_waitcnt vmcnt(6)
	s_waitcnt lgkmcnt(0)
	s_barrier
; #define PG8_STAGE(bufoff, gbase, voff) do { _Pragma("unroll") for (int _i = 0; _i < 2; ++_i) \
;         __builtin_amdgcn_global_load_lds((const unsigned*)((const char*)(gbase) + (voff)[_i]), (LAS unsigned*)(lds + (bufoff) + ldsw + _i * 8192), 16, 0, 0); } while (0)
; #define PG8_LDA(dst, b, h) do { _Pragma("unroll") for (int m = 0; m < 4; ++m) _Pragma("unroll") for (int k = 0; k < 2; ++k) dst[m][k] = *(const LAS bf16x8*)(lds + PG8_SA(b, h) + aoff + m * 2048 + k * 1024); } while (0)
; #define PG8_LDB(dst, b, h) do { _Pragma("unroll") for (int n = 0; n < 2; ++n) _Pragma("unroll") for (int k = 0; k < 2; ++k) dst[n][k] = *(const LAS bf16x8*)(lds + PG8_SB(b, h) + boff + n * 2048 + k * 1024); } while (0)
; #define PG8_WAIT_V(n) asm volatile("s_waitcnt vmcnt(" #n ")" ::: "memory")
; #define PG8_WAIT_L(n) asm volatile("s_waitcnt lgkmcnt(" #n ")" ::: "memory")
; #define PG8_BAR __builtin_amdgcn_s_barrier()
; #define PG8_SCHED __builtin_amdgcn_sched_barrier(0)
; template <class Epi, class Sched, bool I8 = false>
; __device__ __forceinline__ void gemm_phase(LAS unsigned char* lds, const Gemm g, const Sched& S, const Epi& E) {
;     ...
;             PG8_WAIT_V(8); PG8_WAIT_L(0); PG8_BAR; PG8_MMA(1, 0, At, B0); PG8_MMA(1, 1, At, B1); PG8_BAR; PG8_SCHED;
;             PG8_LDB(B0, 1, 0); PG8_LDB(B1, 1, 1); PG8_SCHED; PG8_LDA(At, 1, 0); PG8_STAGE(PG8_SA(0, 1), a2 + hstepA, voffA);
;             PG8_WAIT_V(8); PG8_WAIT_L(0); PG8_BAR; PG8_MMA(0, 0, At, B0); PG8_MMA(0, 1, At, B1); PG8_BAR; PG8_SCHED;
	s_setprio 1
	s_waitcnt lgkmcnt(0)
	v_mfma_i32_16x16x64_i8 v[62:65], v[66:69], v[186:189], v[62:65]
	v_mfma_i32_16x16x64_i8 v[58:61], v[74:77], v[186:189], v[58:61]
	v_mfma_i32_16x16x64_i8 v[46:49], v[66:69], v[194:197], v[46:49]
	v_mfma_i32_16x16x64_i8 v[42:45], v[74:77], v[194:197], v[42:45]
	v_mfma_i32_16x16x64_i8 v[30:33], v[66:69], v[202:205], v[30:33]
	v_mfma_i32_16x16x64_i8 v[26:29], v[74:77], v[202:205], v[26:29]
	v_mfma_i32_16x16x64_i8 v[14:17], v[66:69], v[210:213], v[14:17]
	v_mfma_i32_16x16x64_i8 v[10:13], v[74:77], v[210:213], v[10:13]
	v_mfma_i32_16x16x64_i8 v[62:65], v[70:73], v[190:193], v[62:65]
	v_mfma_i32_16x16x64_i8 v[58:61], v[78:81], v[190:193], v[58:61]
	v_mfma_i32_16x16x64_i8 v[46:49], v[70:73], v[198:201], v[46:49]
	v_mfma_i32_16x16x64_i8 v[42:45], v[78:81], v[198:201], v[42:45]
	v_mfma_i32_16x16x64_i8 v[30:33], v[70:73], v[206:209], v[30:33]
	v_mfma_i32_16x16x64_i8 v[26:29], v[78:81], v[206:209], v[26:29]
	v_mfma_i32_16x16x64_i8 v[14:17], v[70:73], v[214:217], v[14:17]
	v_mfma_i32_16x16x64_i8 v[10:13], v[78:81], v[214:217], v[10:13]
	s_setprio 0
	s_setprio 1
	v_mfma_i32_16x16x64_i8 v[54:57], v[146:149], v[186:189], v[54:57]
	v_mfma_i32_16x16x64_i8 v[50:53], v[172:175], v[186:189], v[50:53]
	v_mfma_i32_16x16x64_i8 v[38:41], v[146:149], v[194:197], v[38:41]
	v_mfma_i32_16x16x64_i8 v[34:37], v[172:175], v[194:197], v[34:37]
	v_mfma_i32_16x16x64_i8 v[22:25], v[146:149], v[202:205], v[22:25]
	v_mfma_i32_16x16x64_i8 v[18:21], v[172:175], v[202:205], v[18:21]
	v_mfma_i32_16x16x64_i8 v[6:9], v[146:149], v[210:213], v[6:9]
	v_mfma_i32_16x16x64_i8 v[2:5], v[172:175], v[210:213], v[2:5]
	v_mfma_i32_16x16x64_i8 v[54:57], v[150:153], v[190:193], v[54:57]
	v_mfma_i32_16x16x64_i8 v[50:53], v[182:185], v[190:193], v[50:53]
	v_mfma_i32_16x16x64_i8 v[38:41], v[150:153], v[198:201], v[38:41]
	v_mfma_i32_16x16x64_i8 v[34:37], v[182:185], v[198:201], v[34:37]
	v_mfma_i32_16x16x64_i8 v[22:25], v[150:153], v[206:209], v[22:25]
	v_mfma_i32_16x16x64_i8 v[18:21], v[182:185], v[206:209], v[18:21]
	v_mfma_i32_16x16x64_i8 v[6:9], v[150:153], v[214:217], v[6:9]
	v_mfma_i32_16x16x64_i8 v[2:5], v[182:185], v[214:217], v[2:5]
	s_setprio 0
	s_barrier
	s_add_i32 s52, 0, 0x18000
	s_add_i32 s53, 0, 0x1c000
	v_add_u32_e32 v78, s52, v176
	v_add_u32_e32 v162, s53, v176
	ds_read_b128 v[66:69], v78
	ds_read_b128 v[70:73], v78 offset:1024
	ds_read_b128 v[74:77], v78 offset:2048
	ds_read_b128 v[78:81], v78 offset:3072
	ds_read_b128 v[146:149], v162
	ds_read_b128 v[150:153], v162 offset:1024
	ds_read_b128 v[172:175], v162 offset:2048
	ds_read_b128 v[182:185], v162 offset:3072
	v_lshl_add_u64 v[218:219], s[26:27], 0, v[154:155]
	s_mov_b32 m0, s34
	s_nop 0
	global_load_lds_dwordx4 v[218:219], off
	v_lshl_add_u64 v[218:219], s[26:27], 0, v[158:159]
	s_mov_b32 m0, s35
	s_nop 0
	global_load_lds_dwordx4 v[218:219], off
	s_add_u32 s26, s26, 0x4000
	s_addc_u32 s27, s27, 0
	s_mov_b32 m0, s36
	v_lshl_add_u64 v[218:219], s[26:27], 0, v[154:155]
	ds_read_b128 v[186:189], v180 offset:32768
	ds_read_b128 v[190:193], v180 offset:33792
	ds_read_b128 v[194:197], v180 offset:34816
	ds_read_b128 v[198:201], v180 offset:35840
	ds_read_b128 v[202:205], v180 offset:36864
	ds_read_b128 v[206:209], v180 offset:37888
	ds_read_b128 v[210:213], v180 offset:38912
	ds_read_b128 v[214:217], v180 offset:39936
	global_load_lds_dwordx4 v[218:219], off
	v_lshl_add_u64 v[218:219], s[26:27], 0, v[158:159]
	s_mov_b32 m0, s37
	s_nop 0
	global_load_lds_dwordx4 v[218:219], off
	s_waitcnt vmcnt(8)
	s_waitcnt lgkmcnt(0)
	s_barrier
; #define PG8_STAGE(bufoff, gbase, voff) do { _Pragma("unroll") for (int _i = 0; _i < 2; ++_i) \
;         __builtin_amdgcn_global_load_lds((const unsigned*)((const char*)(gbase) + (voff)[_i]), (LAS unsigned*)(lds + (bufoff) + ldsw + _i * 8192), 16, 0, 0); } while (0)
; #define PG8_LDA(dst, b, h) do { _Pragma("unroll") for (int m = 0; m < 4; ++m) _Pragma("unroll") for (int k = 0; k < 2; ++k) dst[m][k] = *(const LAS bf16x8*)(lds + PG8_SA(b, h) + aoff + m * 2048 + k * 1024); } while (0)
; #define PG8_WAIT_V(n) asm volatile("s_waitcnt vmcnt(" #n ")" ::: "memory")
; #define PG8_WAIT_L(n) asm volatile("s_waitcnt lgkmcnt(" #n ")" ::: "memory")
; #define PG8_BAR __builtin_amdgcn_s_barrier()
; #define PG8_SCHED __builtin_amdgcn_sched_barrier(0)
; template <class Epi, class Sched, bool I8 = false>
; __device__ __forceinline__ void gemm_phase(LAS unsigned char* lds, const Gemm g, const Sched& S, const Epi& E) {
;     ...
;             PG8_WAIT_V(8); PG8_WAIT_L(0); PG8_BAR; PG8_MMA(0, 0, At, B0); PG8_MMA(0, 1, At, B1); PG8_BAR; PG8_SCHED;
;             PG8_LDA(At, 1, 1); PG8_STAGE(PG8_SB(1, 0), b3, voffB); PG8_STAGE(PG8_SB(1, 1), b3 + hstepB, voffB); PG8_STAGE(PG8_SA(1, 0), a3, voffA);
;             PG8_WAIT_V(8); PG8_WAIT_L(0); PG8_BAR; PG8_MMA(1, 0, At, B0); PG8_MMA(1, 1, At, B1); PG8_BAR; PG8_SCHED;
;         }
;         if (wr == 0) PG8_BAR;
	s_setprio 1
	s_waitcnt lgkmcnt(0)
	v_mfma_i32_16x16x64_i8 v[142:145], v[66:69], v[186:189], v[142:145]
	v_mfma_i32_16x16x64_i8 v[138:141], v[74:77], v[186:189], v[138:141]
	v_mfma_i32_16x16x64_i8 v[126:129], v[66:69], v[194:197], v[126:129]
	v_mfma_i32_16x16x64_i8 v[122:125], v[74:77], v[194:197], v[122:125]
	v_mfma_i32_16x16x64_i8 v[110:113], v[66:69], v[202:205], v[110:113]
	v_mfma_i32_16x16x64_i8 v[106:109], v[74:77], v[202:205], v[106:109]
	v_mfma_i32_16x16x64_i8 v[94:97], v[66:69], v[210:213], v[94:97]
	v_mfma_i32_16x16x64_i8 v[90:93], v[74:77], v[210:213], v[90:93]
	v_mfma_i32_16x16x64_i8 v[142:145], v[70:73], v[190:193], v[142:145]
	v_mfma_i32_16x16x64_i8 v[138:141], v[78:81], v[190:193], v[138:141]
	v_mfma_i32_16x16x64_i8 v[126:129], v[70:73], v[198:201], v[126:129]
	v_mfma_i32_16x16x64_i8 v[122:125], v[78:81], v[198:201], v[122:125]
	v_mfma_i32_16x16x64_i8 v[110:113], v[70:73], v[206:209], v[110:113]
	v_mfma_i32_16x16x64_i8 v[106:109], v[78:81], v[206:209], v[106:109]
	v_mfma_i32_16x16x64_i8 v[94:97], v[70:73], v[214:217], v[94:97]
	v_mfma_i32_16x16x64_i8 v[90:93], v[78:81], v[214:217], v[90:93]
	s_setprio 0
	s_setprio 1
	v_mfma_i32_16x16x64_i8 v[134:137], v[146:149], v[186:189], v[134:137]
	v_mfma_i32_16x16x64_i8 v[130:133], v[172:175], v[186:189], v[130:133]
	v_mfma_i32_16x16x64_i8 v[118:121], v[146:149], v[194:197], v[118:121]
	v_mfma_i32_16x16x64_i8 v[114:117], v[172:175], v[194:197], v[114:117]
	v_mfma_i32_16x16x64_i8 v[102:105], v[146:149], v[202:205], v[102:105]
	v_mfma_i32_16x16x64_i8 v[98:101], v[172:175], v[202:205], v[98:101]
	v_mfma_i32_16x16x64_i8 v[86:89], v[146:149], v[210:213], v[86:89]
	v_mfma_i32_16x16x64_i8 v[82:85], v[172:175], v[210:213], v[82:85]
	v_mfma_i32_16x16x64_i8 v[134:137], v[150:153], v[190:193], v[134:137]
	v_mfma_i32_16x16x64_i8 v[130:133], v[182:185], v[190:193], v[130:133]
	v_mfma_i32_16x16x64_i8 v[118:121], v[150:153], v[198:201], v[118:121]
	v_mfma_i32_16x16x64_i8 v[114:117], v[182:185], v[198:201], v[114:117]
	v_mfma_i32_16x16x64_i8 v[102:105], v[150:153], v[206:209], v[102:105]
	v_mfma_i32_16x16x64_i8 v[98:101], v[182:185], v[206:209], v[98:101]
	v_mfma_i32_16x16x64_i8 v[86:89], v[150:153], v[214:217], v[86:89]
	v_mfma_i32_16x16x64_i8 v[82:85], v[182:185], v[214:217], v[82:85]
	s_setprio 0
	s_barrier
	s_add_u32 s26, s24, 0x8000
	s_addc_u32 s27, s25, 0
	s_add_i32 s52, s52, s33
	v_lshl_add_u64 v[218:219], s[26:27], 0, v[156:157]
	s_mov_b32 m0, s52
	ds_read_b128 v[186:189], v180 offset:49152
	ds_read_b128 v[190:193], v180 offset:50176
	ds_read_b128 v[194:197], v180 offset:51200
	ds_read_b128 v[198:201], v180 offset:52224
	ds_read_b128 v[202:205], v180 offset:53248
	ds_read_b128 v[206:209], v180 offset:54272
	ds_read_b128 v[210:213], v180 offset:55296
	ds_read_b128 v[214:217], v180 offset:56320
	global_load_lds_dwordx4 v[218:219], off
	s_add_i32 m0, s52, 0x2000
	s_add_u32 s24, s24, 0xc000
	v_lshl_add_u64 v[218:219], s[26:27], 0, v[160:161]
	s_addc_u32 s25, s25, 0
	s_add_i32 s26, s53, s33
	global_load_lds_dwordx4 v[218:219], off
	v_lshl_add_u64 v[218:219], s[24:25], 0, v[156:157]
	s_mov_b32 m0, s26
	s_nop 0
	global_load_lds_dwordx4 v[218:219], off
	v_lshl_add_u64 v[218:219], s[24:25], 0, v[160:161]
	s_add_i32 m0, s26, 0x2000
	s_nop 0
	global_load_lds_dwordx4 v[218:219], off
	s_waitcnt vmcnt(6)
	s_waitcnt lgkmcnt(0)
	s_barrier
	s_setprio 1
	s_waitcnt lgkmcnt(0)
	v_mfma_i32_16x16x64_i8 v[62:65], v[66:69], v[186:189], v[62:65]
	v_mfma_i32_16x16x64_i8 v[58:61], v[74:77], v[186:189], v[58:61]
	v_mfma_i32_16x16x64_i8 v[46:49], v[66:69], v[194:197], v[46:49]
	v_mfma_i32_16x16x64_i8 v[42:45], v[74:77], v[194:197], v[42:45]
	v_mfma_i32_16x16x64_i8 v[30:33], v[66:69], v[202:205], v[30:33]
	v_mfma_i32_16x16x64_i8 v[26:29], v[74:77], v[202:205], v[26:29]
	v_mfma_i32_16x16x64_i8 v[14:17], v[66:69], v[210:213], v[14:17]
	v_mfma_i32_16x16x64_i8 v[10:13], v[74:77], v[210:213], v[10:13]
	v_mfma_i32_16x16x64_i8 v[62:65], v[70:73], v[190:193], v[62:65]
	v_mfma_i32_16x16x64_i8 v[58:61], v[78:81], v[190:193], v[58:61]
	v_mfma_i32_16x16x64_i8 v[46:49], v[70:73], v[198:201], v[46:49]
	v_mfma_i32_16x16x64_i8 v[42:45], v[78:81], v[198:201], v[42:45]
	v_mfma_i32_16x16x64_i8 v[30:33], v[70:73], v[206:209], v[30:33]
	v_mfma_i32_16x16x64_i8 v[26:29], v[78:81], v[206:209], v[26:29]
	v_mfma_i32_16x16x64_i8 v[14:17], v[70:73], v[214:217], v[14:17]
	v_mfma_i32_16x16x64_i8 v[10:13], v[78:81], v[214:217], v[10:13]
	s_setprio 0
	s_setprio 1
	v_mfma_i32_16x16x64_i8 v[54:57], v[146:149], v[186:189], v[54:57]
	v_mfma_i32_16x16x64_i8 v[50:53], v[172:175], v[186:189], v[50:53]
	v_mfma_i32_16x16x64_i8 v[38:41], v[146:149], v[194:197], v[38:41]
	v_mfma_i32_16x16x64_i8 v[34:37], v[172:175], v[194:197], v[34:37]
	v_mfma_i32_16x16x64_i8 v[22:25], v[146:149], v[202:205], v[22:25]
	v_mfma_i32_16x16x64_i8 v[18:21], v[172:175], v[202:205], v[18:21]
	v_mfma_i32_16x16x64_i8 v[6:9], v[146:149], v[210:213], v[6:9]
	v_mfma_i32_16x16x64_i8 v[2:5], v[172:175], v[210:213], v[2:5]
	v_mfma_i32_16x16x64_i8 v[54:57], v[150:153], v[190:193], v[54:57]
	v_mfma_i32_16x16x64_i8 v[50:53], v[182:185], v[190:193], v[50:53]
	v_mfma_i32_16x16x64_i8 v[38:41], v[150:153], v[198:201], v[38:41]
	v_mfma_i32_16x16x64_i8 v[34:37], v[182:185], v[198:201], v[34:37]
	v_mfma_i32_16x16x64_i8 v[22:25], v[150:153], v[206:209], v[22:25]
	v_mfma_i32_16x16x64_i8 v[18:21], v[182:185], v[206:209], v[18:21]
	v_mfma_i32_16x16x64_i8 v[6:9], v[150:153], v[214:217], v[6:9]
	v_mfma_i32_16x16x64_i8 v[2:5], v[182:185], v[214:217], v[2:5]
	s_setprio 0
	s_barrier
	s_add_i32 s51, s51, 2
	s_add_u32 s20, s20, 0x10000
	s_addc_u32 s21, s21, 0
	s_add_u32 s49, s49, 0x10000
	s_addc_u32 s50, s50, 0
	s_cmpk_gt_u32 s51, 0x53
	s_cbranch_scc0 .LBB0_4168
	s_and_b64 vcc, exec, s[14:15]
	s_cbranch_vccz .LBB0_4171
	s_barrier

; __global__ void __launch_bounds__(512, 2) mk_fwd(Args args) {
	.amdhsa_kernel _Z6mk_fwd4Args
		.amdhsa_group_segment_fixed_size 0
		.amdhsa_private_segment_fixed_size 0
		.amdhsa_kernarg_size 464
		.amdhsa_user_sgpr_count 2
		.amdhsa_user_sgpr_dispatch_ptr 0
		.amdhsa_user_sgpr_queue_ptr 0
		.amdhsa_user_sgpr_kernarg_segment_ptr 1
		.amdhsa_user_sgpr_dispatch_id 0
		.amdhsa_user_sgpr_kernarg_preload_length 0
		.amdhsa_user_sgpr_kernarg_preload_offset 0
		.amdhsa_user_sgpr_private_segment_size 0
		.amdhsa_uses_dynamic_stack 0
		.amdhsa_enable_private_segment 0
		.amdhsa_system_sgpr_workgroup_id_x 1
		.amdhsa_system_sgpr_workgroup_id_y 0
		.amdhsa_system_sgpr_workgroup_id_z 0
		.amdhsa_system_sgpr_workgroup_info 0
		.amdhsa_system_vgpr_workitem_id 0
		.amdhsa_next_free_vgpr 247
		.amdhsa_next_free_sgpr 100
		.amdhsa_accum_offset 248
		.amdhsa_reserve_vcc 1
		.amdhsa_float_round_mode_32 0
		.amdhsa_float_round_mode_16_64 0
		.amdhsa_float_denorm_mode_32 3
		.amdhsa_float_denorm_mode_16_64 3
		.amdhsa_dx10_clamp 1
		.amdhsa_ieee_mode 1
		.amdhsa_fp16_overflow 0
		.amdhsa_tg_split 0
		.amdhsa_exception_fp_ieee_invalid_op 0
		.amdhsa_exception_fp_denorm_src 0
		.amdhsa_exception_fp_ieee_div_zero 0
		.amdhsa_exception_fp_ieee_overflow 0
		.amdhsa_exception_fp_ieee_underflow 0
		.amdhsa_exception_fp_ieee_inexact 0
		.amdhsa_exception_int_div_zero 0
	.end_amdhsa_kernel

; __global__ void __launch_bounds__(512, 2) mk_fwd(Args args) {
amdhsa.kernels:
  - .agpr_count:     0
    .args:
      - .offset:         0
        .size:           208
        .value_kind:     by_value
      - .offset:         208
        .size:           4
        .value_kind:     hidden_block_count_x
      - .offset:         212
        .size:           4
        .value_kind:     hidden_block_count_y
      - .offset:         216
        .size:           4
        .value_kind:     hidden_block_count_z
      - .offset:         220
        .size:           2
        .value_kind:     hidden_group_size_x
      - .offset:         222
        .size:           2
        .value_kind:     hidden_group_size_y
      - .offset:         224
        .size:           2
        .value_kind:     hidden_group_size_z
      - .offset:         226
        .size:           2
        .value_kind:     hidden_remainder_x
      - .offset:         228
        .size:           2
        .value_kind:     hidden_remainder_y
      - .offset:         230
        .size:           2
        .value_kind:     hidden_remainder_z
      - .offset:         248
        .size:           8
        .value_kind:     hidden_global_offset_x
      - .offset:         256
        .size:           8
        .value_kind:     hidden_global_offset_y
      - .offset:         264
        .size:           8
        .value_kind:     hidden_global_offset_z
      - .offset:         272
        .size:           2
        .value_kind:     hidden_grid_dims
      - .offset:         328
        .size:           4
        .value_kind:     hidden_dynamic_lds_size
    .group_segment_fixed_size: 0
    .kernarg_segment_align: 8
    .kernarg_segment_size: 464
    .language:       OpenCL C
    .language_version:
      - 2
      - 0
    .max_flat_workgroup_size: 512
    .name:           _Z6mk_fwd4Args
    .private_segment_fixed_size: 0
    .sgpr_count:     106
    .sgpr_spill_count: 53
    .symbol:         _Z6mk_fwd4Args.kd
    .uniform_work_group_size: 1
    .uses_dynamic_stack: false
    .vgpr_count:     247
    .vgpr_spill_count: 0
    .wavefront_size: 64
